# P0 x->bf16 loop: 16 loads in flight; P5 out-proj epilogue: 32 residual loads hoisted, counted vmcnt
# baseline (speedup 1.0000x reference)
.LBB0_42:
	v_lshl_add_u64 v[6:7], v[64:65], 4, s[16:17]
	s_lshl_b64 s[16:17], s[18:19], 13
	v_lshl_add_u64 v[12:13], v[2:3], 0, s[16:17]
	s_mov_b64 s[98:99], 0x2000
	s_add_u32 s10, s10, s14
	s_addc_u32 s11, s11, s15
	s_add_u32 s4, s4, s6
	s_addc_u32 s5, s5, s7
	v_lshl_add_u64 v[224:225], v[6:7], 0, s[98:99]
	global_load_dwordx4 v[160:163], v[6:7], off
	global_load_dwordx4 v[164:167], v[6:7], off offset:1024
	global_load_dwordx4 v[168:171], v[6:7], off offset:2048
	global_load_dwordx4 v[172:175], v[6:7], off offset:3072
	v_lshl_add_u64 v[226:227], v[224:225], 0, s[98:99]
	global_load_dwordx4 v[176:179], v[224:225], off offset:-4096
	global_load_dwordx4 v[180:183], v[224:225], off offset:-3072
	global_load_dwordx4 v[184:187], v[224:225], off offset:-2048
	global_load_dwordx4 v[188:191], v[224:225], off offset:-1024
	global_load_dwordx4 v[192:195], v[224:225], off
	global_load_dwordx4 v[196:199], v[224:225], off offset:1024
	global_load_dwordx4 v[200:203], v[224:225], off offset:2048
	global_load_dwordx4 v[204:207], v[224:225], off offset:3072
	s_mov_b64 s[98:99], 0x1000
	global_load_dwordx4 v[208:211], v[226:227], off offset:-4096
	global_load_dwordx4 v[212:215], v[226:227], off offset:-3072
	global_load_dwordx4 v[216:219], v[226:227], off offset:-2048
	global_load_dwordx4 v[220:223], v[226:227], off offset:-1024
	v_lshl_add_u64 v[228:229], v[12:13], 0, s[98:99]
	s_waitcnt vmcnt(15)
	v_bfe_u32 v230, v160, 16, 1
	v_bfe_u32 v231, v161, 16, 1
	v_bfe_u32 v232, v162, 16, 1
	v_bfe_u32 v233, v163, 16, 1
	v_add3_u32 v230, v160, v230, s22
	v_add3_u32 v231, v161, v231, s22
	v_add3_u32 v232, v162, v232, s22
	v_add3_u32 v233, v163, v233, s22
	v_lshrrev_b32_e32 v230, 16, v230
	v_lshrrev_b32_e32 v232, 16, v232
	v_and_or_b32 v160, v231, s23, v230
	v_and_or_b32 v161, v233, s23, v232
	global_store_dwordx2 v[12:13], v[160:161], off
	s_waitcnt vmcnt(15)
	v_bfe_u32 v230, v164, 16, 1
	v_bfe_u32 v231, v165, 16, 1
	v_bfe_u32 v232, v166, 16, 1
	v_bfe_u32 v233, v167, 16, 1
	v_add3_u32 v230, v164, v230, s22
	v_add3_u32 v231, v165, v231, s22
	v_add3_u32 v232, v166, v232, s22
	v_add3_u32 v233, v167, v233, s22
	v_lshrrev_b32_e32 v230, 16, v230
	v_lshrrev_b32_e32 v232, 16, v232
	v_and_or_b32 v164, v231, s23, v230
	v_and_or_b32 v165, v233, s23, v232
	global_store_dwordx2 v[12:13], v[164:165], off offset:512
	s_waitcnt vmcnt(15)
	v_bfe_u32 v230, v168, 16, 1
	v_bfe_u32 v231, v169, 16, 1
	v_bfe_u32 v232, v170, 16, 1
	v_bfe_u32 v233, v171, 16, 1
	v_add3_u32 v230, v168, v230, s22
	v_add3_u32 v231, v169, v231, s22
	v_add3_u32 v232, v170, v232, s22
	v_add3_u32 v233, v171, v233, s22
	v_lshrrev_b32_e32 v230, 16, v230
	v_lshrrev_b32_e32 v232, 16, v232
	v_and_or_b32 v168, v231, s23, v230
	v_and_or_b32 v169, v233, s23, v232
	global_store_dwordx2 v[12:13], v[168:169], off offset:1024
	s_waitcnt vmcnt(15)
	v_bfe_u32 v230, v172, 16, 1
	v_bfe_u32 v231, v173, 16, 1
	v_bfe_u32 v232, v174, 16, 1
	v_bfe_u32 v233, v175, 16, 1
	v_add3_u32 v230, v172, v230, s22
	v_add3_u32 v231, v173, v231, s22
	v_add3_u32 v232, v174, v232, s22
	v_add3_u32 v233, v175, v233, s22
	v_lshrrev_b32_e32 v230, 16, v230
	v_lshrrev_b32_e32 v232, 16, v232
	v_and_or_b32 v172, v231, s23, v230
	v_and_or_b32 v173, v233, s23, v232
	global_store_dwordx2 v[12:13], v[172:173], off offset:1536
	s_waitcnt vmcnt(15)
	v_bfe_u32 v230, v176, 16, 1
	v_bfe_u32 v231, v177, 16, 1
	v_bfe_u32 v232, v178, 16, 1
	v_bfe_u32 v233, v179, 16, 1
	v_add3_u32 v230, v176, v230, s22
	v_add3_u32 v231, v177, v231, s22
	v_add3_u32 v232, v178, v232, s22
	v_add3_u32 v233, v179, v233, s22
	v_lshrrev_b32_e32 v230, 16, v230
	v_lshrrev_b32_e32 v232, 16, v232
	v_and_or_b32 v176, v231, s23, v230
	v_and_or_b32 v177, v233, s23, v232
	global_store_dwordx2 v[12:13], v[176:177], off offset:2048
	s_waitcnt vmcnt(15)
	v_bfe_u32 v230, v180, 16, 1
	v_bfe_u32 v231, v181, 16, 1
	v_bfe_u32 v232, v182, 16, 1
	v_bfe_u32 v233, v183, 16, 1
	v_add3_u32 v230, v180, v230, s22
	v_add3_u32 v231, v181, v231, s22
	v_add3_u32 v232, v182, v232, s22
	v_add3_u32 v233, v183, v233, s22
	v_lshrrev_b32_e32 v230, 16, v230
	v_lshrrev_b32_e32 v232, 16, v232
	v_and_or_b32 v180, v231, s23, v230
	v_and_or_b32 v181, v233, s23, v232
	global_store_dwordx2 v[12:13], v[180:181], off offset:2560
	s_waitcnt vmcnt(15)
	v_bfe_u32 v230, v184, 16, 1
	v_bfe_u32 v231, v185, 16, 1
	v_bfe_u32 v232, v186, 16, 1
	v_bfe_u32 v233, v187, 16, 1
	v_add3_u32 v230, v184, v230, s22
	v_add3_u32 v231, v185, v231, s22
	v_add3_u32 v232, v186, v232, s22
	v_add3_u32 v233, v187, v233, s22
	v_lshrrev_b32_e32 v230, 16, v230
	v_lshrrev_b32_e32 v232, 16, v232
	v_and_or_b32 v184, v231, s23, v230
	v_and_or_b32 v185, v233, s23, v232
	global_store_dwordx2 v[12:13], v[184:185], off offset:3072
	s_waitcnt vmcnt(15)
	v_bfe_u32 v230, v188, 16, 1
	v_bfe_u32 v231, v189, 16, 1
	v_bfe_u32 v232, v190, 16, 1
	v_bfe_u32 v233, v191, 16, 1
	v_add3_u32 v230, v188, v230, s22
	v_add3_u32 v231, v189, v231, s22
	v_add3_u32 v232, v190, v232, s22
	v_add3_u32 v233, v191, v233, s22
	v_lshrrev_b32_e32 v230, 16, v230
	v_lshrrev_b32_e32 v232, 16, v232
	v_and_or_b32 v188, v231, s23, v230
	v_and_or_b32 v189, v233, s23, v232
	global_store_dwordx2 v[12:13], v[188:189], off offset:3584
	s_waitcnt vmcnt(15)
	v_bfe_u32 v230, v192, 16, 1
	v_bfe_u32 v231, v193, 16, 1
	v_bfe_u32 v232, v194, 16, 1
	v_bfe_u32 v233, v195, 16, 1
	v_add3_u32 v230, v192, v230, s22
	v_add3_u32 v231, v193, v231, s22
	v_add3_u32 v232, v194, v232, s22
	v_add3_u32 v233, v195, v233, s22
	v_lshrrev_b32_e32 v230, 16, v230
	v_lshrrev_b32_e32 v232, 16, v232
	v_and_or_b32 v192, v231, s23, v230
	v_and_or_b32 v193, v233, s23, v232
	global_store_dwordx2 v[228:229], v[192:193], off
	s_waitcnt vmcnt(15)
	v_bfe_u32 v230, v196, 16, 1
	v_bfe_u32 v231, v197, 16, 1
	v_bfe_u32 v232, v198, 16, 1
	v_bfe_u32 v233, v199, 16, 1
	v_add3_u32 v230, v196, v230, s22
	v_add3_u32 v231, v197, v231, s22
	v_add3_u32 v232, v198, v232, s22
	v_add3_u32 v233, v199, v233, s22
	v_lshrrev_b32_e32 v230, 16, v230
	v_lshrrev_b32_e32 v232, 16, v232
	v_and_or_b32 v196, v231, s23, v230
	v_and_or_b32 v197, v233, s23, v232
	global_store_dwordx2 v[228:229], v[196:197], off offset:512
	s_waitcnt vmcnt(15)
	v_bfe_u32 v230, v200, 16, 1
	v_bfe_u32 v231, v201, 16, 1
	v_bfe_u32 v232, v202, 16, 1
	v_bfe_u32 v233, v203, 16, 1
	v_add3_u32 v230, v200, v230, s22
	v_add3_u32 v231, v201, v231, s22
	v_add3_u32 v232, v202, v232, s22
	v_add3_u32 v233, v203, v233, s22
	v_lshrrev_b32_e32 v230, 16, v230
	v_lshrrev_b32_e32 v232, 16, v232
	v_and_or_b32 v200, v231, s23, v230
	v_and_or_b32 v201, v233, s23, v232
	global_store_dwordx2 v[228:229], v[200:201], off offset:1024
	s_waitcnt vmcnt(15)
	v_bfe_u32 v230, v204, 16, 1
	v_bfe_u32 v231, v205, 16, 1
	v_bfe_u32 v232, v206, 16, 1
	v_bfe_u32 v233, v207, 16, 1
	v_add3_u32 v230, v204, v230, s22
	v_add3_u32 v231, v205, v231, s22
	v_add3_u32 v232, v206, v232, s22
	v_add3_u32 v233, v207, v233, s22
	v_lshrrev_b32_e32 v230, 16, v230
	v_lshrrev_b32_e32 v232, 16, v232
	v_and_or_b32 v204, v231, s23, v230
	v_and_or_b32 v205, v233, s23, v232
	global_store_dwordx2 v[228:229], v[204:205], off offset:1536
	s_waitcnt vmcnt(15)
	v_bfe_u32 v230, v208, 16, 1
	v_bfe_u32 v231, v209, 16, 1
	v_bfe_u32 v232, v210, 16, 1
	v_bfe_u32 v233, v211, 16, 1
	v_add3_u32 v230, v208, v230, s22
	v_add3_u32 v231, v209, v231, s22
	v_add3_u32 v232, v210, v232, s22
	v_add3_u32 v233, v211, v233, s22
	v_lshrrev_b32_e32 v230, 16, v230
	v_lshrrev_b32_e32 v232, 16, v232
	v_and_or_b32 v208, v231, s23, v230
	v_and_or_b32 v209, v233, s23, v232
	global_store_dwordx2 v[228:229], v[208:209], off offset:2048
	s_waitcnt vmcnt(15)
	v_bfe_u32 v230, v212, 16, 1
	v_bfe_u32 v231, v213, 16, 1
	v_bfe_u32 v232, v214, 16, 1
	v_bfe_u32 v233, v215, 16, 1
	v_add3_u32 v230, v212, v230, s22
	v_add3_u32 v231, v213, v231, s22
	v_add3_u32 v232, v214, v232, s22
	v_add3_u32 v233, v215, v233, s22
	v_lshrrev_b32_e32 v230, 16, v230
	v_lshrrev_b32_e32 v232, 16, v232
	v_and_or_b32 v212, v231, s23, v230
	v_and_or_b32 v213, v233, s23, v232
	global_store_dwordx2 v[228:229], v[212:213], off offset:2560
	s_waitcnt vmcnt(15)
	v_bfe_u32 v230, v216, 16, 1
	v_bfe_u32 v231, v217, 16, 1
	v_bfe_u32 v232, v218, 16, 1
	v_bfe_u32 v233, v219, 16, 1
	v_add3_u32 v230, v216, v230, s22
	v_add3_u32 v231, v217, v231, s22
	v_add3_u32 v232, v218, v232, s22
	v_add3_u32 v233, v219, v233, s22
	v_lshrrev_b32_e32 v230, 16, v230
	v_lshrrev_b32_e32 v232, 16, v232
	v_and_or_b32 v216, v231, s23, v230
	v_and_or_b32 v217, v233, s23, v232
	global_store_dwordx2 v[228:229], v[216:217], off offset:3072
	s_waitcnt vmcnt(15)
	v_bfe_u32 v230, v220, 16, 1
	v_bfe_u32 v231, v221, 16, 1
	v_bfe_u32 v232, v222, 16, 1
	v_bfe_u32 v233, v223, 16, 1
	v_add3_u32 v230, v220, v230, s22
	v_add3_u32 v231, v221, v231, s22
	v_add3_u32 v232, v222, v232, s22
	v_add3_u32 v233, v223, v233, s22
	v_lshrrev_b32_e32 v230, 16, v230
	v_lshrrev_b32_e32 v232, 16, v232
	v_and_or_b32 v220, v231, s23, v230
	v_and_or_b32 v221, v233, s23, v232
	global_store_dwordx2 v[228:229], v[220:221], off offset:3584
	s_cmpk_gt_i32 s10, 0x23ff
	s_cbranch_scc1 .LBB0_47

.LBB0_1157:
	s_lshl_b32 s27, s42, 8
	v_lshl_add_u32 v140, s26, 8, v154
	s_cmp_lt_i32 s20, 0
	s_mov_b64 s[42:43], -1
	v_ashrrev_i32_e32 v141, 31, v140
	s_cbranch_scc0 .LBB0_1176
	v_add_u32_e32 v142, s27, v152
	v_ashrrev_i32_e32 v143, 31, v142
	v_lshlrev_b64 v[144:145], 12, v[142:143]
	v_lshl_add_u64 v[144:145], v[144:145], 0, v[140:141]
	v_lshlrev_b64 v[146:147], 1, v[144:145]
	v_lshl_add_u64 v[148:149], s[0:1], 0, v[146:147]
	s_mov_b64 s[98:99], 0x20000
	s_mov_b64 s[100:101], 0xa0000
	global_load_dwordx2 v[184:185], v[148:149], off
	global_load_dwordx2 v[186:187], v[148:149], off offset:32
	global_load_dwordx2 v[188:189], v[148:149], off offset:256
	global_load_dwordx2 v[190:191], v[148:149], off offset:288
	v_lshl_add_u64 v[248:249], v[148:149], 0, s[98:99]
	global_load_dwordx2 v[192:193], v[248:249], off
	global_load_dwordx2 v[194:195], v[248:249], off offset:32
	global_load_dwordx2 v[196:197], v[248:249], off offset:256
	global_load_dwordx2 v[198:199], v[248:249], off offset:288
	v_lshl_add_u64 v[248:249], v[248:249], 0, s[98:99]
	global_load_dwordx2 v[200:201], v[248:249], off
	global_load_dwordx2 v[202:203], v[248:249], off offset:32
	global_load_dwordx2 v[204:205], v[248:249], off offset:256
	global_load_dwordx2 v[206:207], v[248:249], off offset:288
	v_lshl_add_u64 v[248:249], v[248:249], 0, s[98:99]
	global_load_dwordx2 v[208:209], v[248:249], off
	global_load_dwordx2 v[210:211], v[248:249], off offset:32
	global_load_dwordx2 v[212:213], v[248:249], off offset:256
	global_load_dwordx2 v[214:215], v[248:249], off offset:288
	v_lshl_add_u64 v[248:249], v[248:249], 0, s[100:101]
	global_load_dwordx2 v[216:217], v[248:249], off
	global_load_dwordx2 v[218:219], v[248:249], off offset:32
	global_load_dwordx2 v[220:221], v[248:249], off offset:256
	global_load_dwordx2 v[222:223], v[248:249], off offset:288
	v_lshl_add_u64 v[248:249], v[248:249], 0, s[98:99]
	global_load_dwordx2 v[224:225], v[248:249], off
	global_load_dwordx2 v[226:227], v[248:249], off offset:32
	global_load_dwordx2 v[228:229], v[248:249], off offset:256
	global_load_dwordx2 v[230:231], v[248:249], off offset:288
	v_lshl_add_u64 v[248:249], v[248:249], 0, s[98:99]
	global_load_dwordx2 v[232:233], v[248:249], off
	global_load_dwordx2 v[234:235], v[248:249], off offset:32
	global_load_dwordx2 v[236:237], v[248:249], off offset:256
	global_load_dwordx2 v[238:239], v[248:249], off offset:288
	v_lshl_add_u64 v[248:249], v[248:249], 0, s[98:99]
	global_load_dwordx2 v[240:241], v[248:249], off
	global_load_dwordx2 v[242:243], v[248:249], off offset:32
	global_load_dwordx2 v[244:245], v[248:249], off offset:256
	global_load_dwordx2 v[246:247], v[248:249], off offset:288
	v_lshl_add_u64 v[146:147], s[6:7], 0, v[146:147]
	v_lshl_add_u64 v[144:145], s[10:11], 0, v[144:145]
	s_waitcnt vmcnt(31)
	v_mov_b32_e32 v150, v184
	v_mov_b32_e32 v151, v185
	v_lshlrev_b32_e32 v162, 16, v150
	v_and_b32_e32 v163, 0xffff0000, v150
	v_lshlrev_b32_e32 v150, 16, v151
	v_and_b32_e32 v151, 0xffff0000, v151
	v_pk_fma_f32 v[162:163], v[162:163], s[24:25], v[124:125] op_sel_hi:[1,0,1]
	v_pk_fma_f32 v[150:151], v[150:151], s[24:25], v[126:127] op_sel_hi:[1,0,1]
	v_mul_f32_e32 v161, 0x417e0000, v163
	v_mul_f32_e32 v133, 0x417e0000, v162
	v_mul_f32_e32 v166, 0x417e0000, v150
	v_mul_f32_e32 v167, 0x417e0000, v151
	v_med3_f32 v161, v161, s64, v160
	v_med3_f32 v133, v133, s64, v160
	v_med3_f32 v166, v166, s64, v160
	v_med3_f32 v167, v167, s64, v160
	v_rndne_f32_e32 v161, v161
	v_rndne_f32_e32 v133, v133
	v_rndne_f32_e32 v166, v166
	v_rndne_f32_e32 v167, v167
	v_cvt_i32_f32_e32 v161, v161
	v_cvt_i32_f32_e32 v133, v133
	v_cvt_i32_f32_sdwa v166, v166 dst_sel:WORD_1 dst_unused:UNUSED_PAD src0_sel:DWORD
	v_cvt_i32_f32_e32 v167, v167
	v_cvt_pk_bf16_f32 v164, v162, v163
	v_lshlrev_b32_e32 v161, 8, v161
	v_cvt_pk_bf16_f32 v165, v150, v151
	global_store_dwordx2 v[146:147], v[164:165], off
	v_and_b32_e32 v164, 0xff0000, v166
	v_perm_b32 v133, v167, v133, s65
	v_and_b32_e32 v161, 0xff00, v161
	v_or3_b32 v133, v133, v161, v164
	global_store_dword v[144:145], v133, off
	v_mul_f32_e32 v177, v162, v162
	v_mul_f32_e32 v179, v150, v150
	s_waitcnt vmcnt(32)
	v_mov_b32_e32 v164, v186
	v_mov_b32_e32 v165, v187
	v_lshlrev_b32_e32 v166, 16, v164
	v_and_b32_e32 v167, 0xffff0000, v164
	v_lshlrev_b32_e32 v164, 16, v165
	v_and_b32_e32 v165, 0xffff0000, v165
	v_pk_fma_f32 v[166:167], v[166:167], s[24:25], v[120:121] op_sel_hi:[1,0,1]
	v_pk_fma_f32 v[164:165], v[164:165], s[24:25], v[122:123] op_sel_hi:[1,0,1]
	v_mul_f32_e32 v161, 0x417e0000, v167
	v_mul_f32_e32 v133, 0x417e0000, v166
	v_mul_f32_e32 v170, 0x417e0000, v164
	v_mul_f32_e32 v171, 0x417e0000, v165
	v_med3_f32 v161, v161, s64, v160
	v_med3_f32 v133, v133, s64, v160
	v_med3_f32 v170, v170, s64, v160
	v_med3_f32 v171, v171, s64, v160
	v_rndne_f32_e32 v161, v161
	v_rndne_f32_e32 v133, v133
	v_rndne_f32_e32 v170, v170
	v_rndne_f32_e32 v171, v171
	v_cvt_i32_f32_e32 v161, v161
	v_cvt_i32_f32_e32 v133, v133
	v_cvt_i32_f32_sdwa v170, v170 dst_sel:WORD_1 dst_unused:UNUSED_PAD src0_sel:DWORD
	v_cvt_i32_f32_e32 v171, v171
	v_cvt_pk_bf16_f32 v168, v166, v167
	v_lshlrev_b32_e32 v161, 8, v161
	v_cvt_pk_bf16_f32 v169, v164, v165
	global_store_dwordx2 v[146:147], v[168:169], off offset:32
	v_and_b32_e32 v168, 0xff0000, v170
	v_perm_b32 v133, v171, v133, s65
	v_and_b32_e32 v161, 0xff00, v161
	v_or3_b32 v133, v133, v161, v168
	global_store_dword v[144:145], v133, off offset:16
	v_mul_f32_e32 v180, v164, v164
	v_mov_b32_e32 v176, v166
	v_mov_b32_e32 v178, v164
	s_waitcnt vmcnt(33)
	v_mov_b32_e32 v168, v188
	v_mov_b32_e32 v169, v189
	v_lshlrev_b32_e32 v170, 16, v168
	v_and_b32_e32 v171, 0xffff0000, v168
	v_lshlrev_b32_e32 v168, 16, v169
	v_and_b32_e32 v169, 0xffff0000, v169
	v_pk_fma_f32 v[170:171], v[170:171], s[24:25], v[112:113] op_sel_hi:[1,0,1]
	v_pk_fma_f32 v[168:169], v[168:169], s[24:25], v[114:115] op_sel_hi:[1,0,1]
	v_mul_f32_e32 v161, 0x417e0000, v171
	v_mul_f32_e32 v133, 0x417e0000, v170
	v_mul_f32_e32 v174, 0x417e0000, v168
	v_mul_f32_e32 v175, 0x417e0000, v169
	v_med3_f32 v161, v161, s64, v160
	v_med3_f32 v133, v133, s64, v160
	v_med3_f32 v174, v174, s64, v160
	v_med3_f32 v175, v175, s64, v160
	v_rndne_f32_e32 v161, v161
	v_rndne_f32_e32 v133, v133
	v_rndne_f32_e32 v174, v174
	v_rndne_f32_e32 v175, v175
	v_cvt_i32_f32_e32 v161, v161
	v_cvt_i32_f32_e32 v133, v133
	v_cvt_i32_f32_sdwa v174, v174 dst_sel:WORD_1 dst_unused:UNUSED_PAD src0_sel:DWORD
	v_cvt_i32_f32_e32 v175, v175
	v_cvt_pk_bf16_f32 v172, v170, v171
	v_lshlrev_b32_e32 v161, 8, v161
	v_cvt_pk_bf16_f32 v173, v168, v169
	global_store_dwordx2 v[146:147], v[172:173], off offset:256
	v_and_b32_e32 v172, 0xff0000, v174
	v_perm_b32 v133, v175, v133, s65
	v_and_b32_e32 v161, 0xff00, v161
	v_or3_b32 v133, v133, v161, v172
	global_store_dword v[144:145], v133, off offset:128
	v_add_f32_e32 v172, v162, v163
	v_add_f32_e32 v174, v150, v151
	v_mul_f32_e32 v163, v163, v163
	v_mul_f32_e32 v151, v151, v151
	v_mul_f32_e32 v173, v166, v166
	v_mul_f32_e32 v175, v167, v167
	v_mov_b32_e32 v162, v167
	v_mov_b32_e32 v150, v165
	v_pk_fma_f32 v[164:165], v[164:165], v[164:165], v[180:181] op_sel_hi:[1,1,0]
	v_pk_add_f32 v[162:163], v[176:177], v[162:163]
	v_pk_add_f32 v[150:151], v[178:179], v[150:151]
	v_pk_add_f32 v[166:167], v[172:173], v[174:175]
	v_mov_b32_e32 v133, v165
	v_pk_add_f32 v[150:151], v[162:163], v[150:151]
	v_pk_add_f32 v[162:163], v[166:167], v[132:133]
	v_mul_f32_e32 v165, v171, v171
	v_pk_add_f32 v[150:151], v[150:151], v[162:163]
	v_mul_f32_e32 v163, v170, v170
	v_mul_f32_e32 v167, v168, v168
	v_mul_f32_e32 v173, v169, v169
	v_mov_b32_e32 v162, v170
	v_mov_b32_e32 v164, v171
	v_mov_b32_e32 v166, v168
	v_mov_b32_e32 v172, v169
	v_pk_add_f32 v[162:163], v[162:163], v[164:165]
	v_pk_add_f32 v[164:165], v[166:167], v[172:173]
	s_nop 0
	v_pk_add_f32 v[162:163], v[162:163], v[164:165]
	s_nop 0
	v_pk_add_f32 v[150:151], v[150:151], v[162:163]
	s_waitcnt vmcnt(34)
	v_mov_b32_e32 v148, v190
	v_mov_b32_e32 v149, v191
	v_lshlrev_b32_e32 v162, 16, v148
	v_and_b32_e32 v163, 0xffff0000, v148
	v_lshlrev_b32_e32 v148, 16, v149
	v_and_b32_e32 v149, 0xffff0000, v149
	v_pk_fma_f32 v[148:149], v[148:149], s[24:25], v[106:107] op_sel_hi:[1,0,1]
	v_pk_fma_f32 v[162:163], v[162:163], s[24:25], v[104:105] op_sel_hi:[1,0,1]
	v_mul_f32_e32 v171, v148, v148
	v_mul_f32_e32 v167, v162, v162
	v_mul_f32_e32 v169, v163, v163
	v_mul_f32_e32 v173, v149, v149
	v_mov_b32_e32 v166, v162
	v_mov_b32_e32 v168, v163
	v_mov_b32_e32 v170, v148
	v_mov_b32_e32 v172, v149
	v_cvt_pk_bf16_f32 v164, v162, v163
	v_cvt_pk_bf16_f32 v165, v148, v149
	v_mul_f32_e32 v174, 0x417e0000, v148
	v_mul_f32_e32 v175, 0x417e0000, v149
	global_store_dwordx2 v[146:147], v[164:165], off offset:288
	v_pk_add_f32 v[146:147], v[166:167], v[168:169]
	v_pk_add_f32 v[148:149], v[170:171], v[172:173]
	v_mul_f32_e32 v161, 0x417e0000, v163
	v_pk_add_f32 v[146:147], v[146:147], v[148:149]
	v_mul_f32_e32 v133, 0x417e0000, v162
	v_pk_add_f32 v[146:147], v[150:151], v[146:147]
	ds_swizzle_b32 v148, v146 offset:swizzle(SWAP,16)
	ds_swizzle_b32 v149, v147 offset:swizzle(SWAP,16)
	v_med3_f32 v161, v161, s64, v160
	v_med3_f32 v133, v133, s64, v160
	v_med3_f32 v162, v174, s64, v160
	v_med3_f32 v163, v175, s64, v160
	v_rndne_f32_e32 v161, v161
	v_rndne_f32_e32 v133, v133
	v_rndne_f32_e32 v162, v162
	v_rndne_f32_e32 v163, v163
	v_cvt_i32_f32_e32 v161, v161
	v_cvt_i32_f32_e32 v133, v133
	v_cvt_i32_f32_sdwa v150, v162 dst_sel:WORD_1 dst_unused:UNUSED_PAD src0_sel:DWORD
	v_cvt_i32_f32_e32 v151, v163
	s_waitcnt lgkmcnt(0)
	v_pk_add_f32 v[146:147], v[146:147], v[148:149]
	ds_bpermute_b32 v148, v155, v146
	ds_bpermute_b32 v149, v155, v147
	v_lshlrev_b32_e32 v161, 8, v161
	v_and_b32_e32 v161, 0xff00, v161
	v_and_b32_e32 v150, 0xff0000, v150
	v_perm_b32 v133, v151, v133, s65
	v_or3_b32 v133, v133, v161, v150
	global_store_dword v[144:145], v133, off offset:144
	s_and_saveexec_b64 s[42:43], s[16:17]
	s_cbranch_execz .LBB0_1160
	s_lshl_b32 s44, s26, 2
	s_waitcnt lgkmcnt(0)
	v_pk_add_f32 v[144:145], v[146:147], v[148:149]
	v_lshlrev_b64 v[146:147], 6, v[142:143]
	s_ashr_i32 s45, s44, 31
	v_lshl_add_u64 v[146:147], v[146:147], 0, s[44:45]
	v_or_b32_e32 v146, s3, v146
	v_lshl_add_u64 v[146:147], v[146:147], 3, s[8:9]
	global_store_dwordx2 v[146:147], v[144:145], off
.LBB0_1160:
	s_or_b64 exec, exec, s[42:43]
	v_or_b32_e32 v144, 16, v142
	v_ashrrev_i32_e32 v145, 31, v144
	v_lshlrev_b64 v[146:147], 12, v[144:145]
	v_lshl_add_u64 v[146:147], v[146:147], 0, v[140:141]
	s_waitcnt lgkmcnt(0)
	v_lshlrev_b64 v[148:149], 1, v[146:147]
	v_lshl_add_u64 v[150:151], s[0:1], 0, v[148:149]
	v_lshl_add_u64 v[146:147], s[10:11], 0, v[146:147]
	v_lshl_add_u64 v[148:149], s[6:7], 0, v[148:149]
	s_waitcnt vmcnt(35)
	v_mov_b32_e32 v162, v192
	v_mov_b32_e32 v163, v193
	v_lshlrev_b32_e32 v164, 16, v162
	v_and_b32_e32 v165, 0xffff0000, v162
	v_lshlrev_b32_e32 v162, 16, v163
	v_and_b32_e32 v163, 0xffff0000, v163
	v_pk_fma_f32 v[164:165], v[164:165], s[24:25], v[116:117] op_sel_hi:[1,0,1]
	v_pk_fma_f32 v[162:163], v[162:163], s[24:25], v[118:119] op_sel_hi:[1,0,1]
	v_mul_f32_e32 v143, 0x417e0000, v165
	v_mul_f32_e32 v133, 0x417e0000, v164
	v_mul_f32_e32 v161, 0x417e0000, v162
	v_mul_f32_e32 v168, 0x417e0000, v163
	v_med3_f32 v143, v143, s64, v160
	v_med3_f32 v133, v133, s64, v160
	v_med3_f32 v161, v161, s64, v160
	v_med3_f32 v168, v168, s64, v160
	v_rndne_f32_e32 v143, v143
	v_rndne_f32_e32 v133, v133
	v_rndne_f32_e32 v161, v161
	v_rndne_f32_e32 v168, v168
	v_cvt_i32_f32_e32 v143, v143
	v_cvt_i32_f32_e32 v133, v133
	v_cvt_i32_f32_sdwa v161, v161 dst_sel:WORD_1 dst_unused:UNUSED_PAD src0_sel:DWORD
	v_cvt_i32_f32_e32 v168, v168
	v_lshlrev_b32_e32 v143, 8, v143
	v_and_b32_e32 v143, 0xff00, v143
	v_and_b32_e32 v161, 0xff0000, v161
	v_perm_b32 v133, v168, v133, s65
	v_or3_b32 v133, v133, v143, v161
	v_cvt_pk_bf16_f32 v166, v164, v165
	v_cvt_pk_bf16_f32 v167, v162, v163
	global_store_dwordx2 v[148:149], v[166:167], off
	global_store_dword v[146:147], v133, off
	v_mul_f32_e32 v179, v164, v164
	v_mul_f32_e32 v181, v162, v162
	s_waitcnt vmcnt(36)
	v_mov_b32_e32 v166, v194
	v_mov_b32_e32 v167, v195
	v_lshlrev_b32_e32 v168, 16, v166
	v_and_b32_e32 v169, 0xffff0000, v166
	v_lshlrev_b32_e32 v166, 16, v167
	v_and_b32_e32 v167, 0xffff0000, v167
	v_pk_fma_f32 v[168:169], v[168:169], s[24:25], v[108:109] op_sel_hi:[1,0,1]
	v_pk_fma_f32 v[166:167], v[166:167], s[24:25], v[110:111] op_sel_hi:[1,0,1]
	v_mul_f32_e32 v143, 0x417e0000, v169
	v_mul_f32_e32 v133, 0x417e0000, v168
	v_mul_f32_e32 v161, 0x417e0000, v166
	v_mul_f32_e32 v172, 0x417e0000, v167
	v_med3_f32 v143, v143, s64, v160
	v_med3_f32 v133, v133, s64, v160
	v_med3_f32 v161, v161, s64, v160
	v_med3_f32 v172, v172, s64, v160
	v_rndne_f32_e32 v143, v143
	v_rndne_f32_e32 v133, v133
	v_rndne_f32_e32 v161, v161
	v_rndne_f32_e32 v172, v172
	v_cvt_i32_f32_e32 v143, v143
	v_cvt_i32_f32_e32 v133, v133
	v_cvt_i32_f32_sdwa v161, v161 dst_sel:WORD_1 dst_unused:UNUSED_PAD src0_sel:DWORD
	v_cvt_i32_f32_e32 v172, v172
	v_lshlrev_b32_e32 v143, 8, v143
	v_and_b32_e32 v143, 0xff00, v143
	v_and_b32_e32 v161, 0xff0000, v161
	v_perm_b32 v133, v172, v133, s65
	v_or3_b32 v133, v133, v143, v161
	v_cvt_pk_bf16_f32 v170, v168, v169
	v_cvt_pk_bf16_f32 v171, v166, v167
	global_store_dwordx2 v[148:149], v[170:171], off offset:32
	global_store_dword v[146:147], v133, off offset:16
	v_mul_f32_e32 v182, v166, v166
	v_mul_f32_e32 v177, v169, v169
	v_mov_b32_e32 v178, v168
	v_mov_b32_e32 v180, v166
	s_waitcnt vmcnt(37)
	v_mov_b32_e32 v170, v196
	v_mov_b32_e32 v171, v197
	v_lshlrev_b32_e32 v172, 16, v170
	v_and_b32_e32 v173, 0xffff0000, v170
	v_lshlrev_b32_e32 v170, 16, v171
	v_and_b32_e32 v171, 0xffff0000, v171
	v_pk_fma_f32 v[172:173], v[172:173], s[24:25], v[96:97] op_sel_hi:[1,0,1]
	v_pk_fma_f32 v[170:171], v[170:171], s[24:25], v[98:99] op_sel_hi:[1,0,1]
	v_mul_f32_e32 v143, 0x417e0000, v173
	v_mul_f32_e32 v133, 0x417e0000, v172
	v_mul_f32_e32 v161, 0x417e0000, v170
	v_mul_f32_e32 v176, 0x417e0000, v171
	v_med3_f32 v143, v143, s64, v160
	v_med3_f32 v133, v133, s64, v160
	v_med3_f32 v161, v161, s64, v160
	v_med3_f32 v176, v176, s64, v160
	v_rndne_f32_e32 v143, v143
	v_rndne_f32_e32 v133, v133
	v_rndne_f32_e32 v161, v161
	v_rndne_f32_e32 v176, v176
	v_cvt_i32_f32_e32 v143, v143
	v_cvt_i32_f32_e32 v133, v133
	v_cvt_i32_f32_sdwa v161, v161 dst_sel:WORD_1 dst_unused:UNUSED_PAD src0_sel:DWORD
	v_cvt_i32_f32_e32 v176, v176
	v_lshlrev_b32_e32 v143, 8, v143
	v_and_b32_e32 v143, 0xff00, v143
	v_and_b32_e32 v161, 0xff0000, v161
	v_perm_b32 v133, v176, v133, s65
	v_or3_b32 v133, v133, v143, v161
	v_cvt_pk_bf16_f32 v174, v172, v173
	v_cvt_pk_bf16_f32 v175, v170, v171
	global_store_dwordx2 v[148:149], v[174:175], off offset:256
	global_store_dword v[146:147], v133, off offset:128
	v_add_f32_e32 v174, v164, v165
	v_add_f32_e32 v176, v162, v163
	v_mul_f32_e32 v165, v165, v165
	v_mul_f32_e32 v163, v163, v163
	v_mul_f32_e32 v175, v168, v168
	v_mov_b32_e32 v164, v169
	v_mov_b32_e32 v162, v167
	v_pk_fma_f32 v[166:167], v[166:167], v[166:167], v[182:183] op_sel_hi:[1,1,0]
	v_pk_add_f32 v[164:165], v[178:179], v[164:165]
	v_pk_add_f32 v[162:163], v[180:181], v[162:163]
	v_pk_add_f32 v[168:169], v[174:175], v[176:177]
	v_mov_b32_e32 v133, v167
	v_pk_add_f32 v[162:163], v[164:165], v[162:163]
	v_pk_add_f32 v[164:165], v[168:169], v[132:133]
	v_mul_f32_e32 v167, v173, v173
	v_pk_add_f32 v[162:163], v[162:163], v[164:165]
	v_mul_f32_e32 v165, v172, v172
	v_mul_f32_e32 v169, v170, v170
	v_mul_f32_e32 v175, v171, v171
	v_mov_b32_e32 v164, v172
	v_mov_b32_e32 v166, v173
	v_mov_b32_e32 v168, v170
	v_mov_b32_e32 v174, v171
	v_pk_add_f32 v[164:165], v[164:165], v[166:167]
	v_pk_add_f32 v[166:167], v[168:169], v[174:175]
	s_nop 0
	v_pk_add_f32 v[164:165], v[164:165], v[166:167]
	s_nop 0
	v_pk_add_f32 v[162:163], v[162:163], v[164:165]
	s_waitcnt vmcnt(38)
	v_mov_b32_e32 v150, v198
	v_mov_b32_e32 v151, v199
	v_lshlrev_b32_e32 v164, 16, v150
	v_and_b32_e32 v165, 0xffff0000, v150
	v_lshlrev_b32_e32 v150, 16, v151
	v_and_b32_e32 v151, 0xffff0000, v151
	v_pk_fma_f32 v[150:151], v[150:151], s[24:25], v[90:91] op_sel_hi:[1,0,1]
	v_pk_fma_f32 v[164:165], v[164:165], s[24:25], v[88:89] op_sel_hi:[1,0,1]
	v_mul_f32_e32 v173, v150, v150
	v_mul_f32_e32 v169, v164, v164
	v_mul_f32_e32 v171, v165, v165
	v_mul_f32_e32 v175, v151, v151
	v_mov_b32_e32 v168, v164
	v_mov_b32_e32 v170, v165
	v_mov_b32_e32 v172, v150
	v_mov_b32_e32 v174, v151
	v_cvt_pk_bf16_f32 v166, v164, v165
	v_cvt_pk_bf16_f32 v167, v150, v151
	v_mul_f32_e32 v161, 0x417e0000, v150
	v_mul_f32_e32 v176, 0x417e0000, v151
	global_store_dwordx2 v[148:149], v[166:167], off offset:288
	v_pk_add_f32 v[148:149], v[168:169], v[170:171]
	v_pk_add_f32 v[150:151], v[172:173], v[174:175]
	v_mul_f32_e32 v143, 0x417e0000, v165
	v_pk_add_f32 v[148:149], v[148:149], v[150:151]
	v_mul_f32_e32 v133, 0x417e0000, v164
	v_pk_add_f32 v[148:149], v[162:163], v[148:149]
	ds_swizzle_b32 v150, v148 offset:swizzle(SWAP,16)
	ds_swizzle_b32 v151, v149 offset:swizzle(SWAP,16)
	v_med3_f32 v143, v143, s64, v160
	v_med3_f32 v133, v133, s64, v160
	v_med3_f32 v161, v161, s64, v160
	v_med3_f32 v164, v176, s64, v160
	v_rndne_f32_e32 v143, v143
	v_rndne_f32_e32 v133, v133
	v_rndne_f32_e32 v161, v161
	v_rndne_f32_e32 v164, v164
	v_cvt_i32_f32_e32 v143, v143
	v_cvt_i32_f32_e32 v133, v133
	v_cvt_i32_f32_sdwa v161, v161 dst_sel:WORD_1 dst_unused:UNUSED_PAD src0_sel:DWORD
	v_cvt_i32_f32_e32 v162, v164
	s_waitcnt lgkmcnt(0)
	v_pk_add_f32 v[148:149], v[148:149], v[150:151]
	ds_bpermute_b32 v150, v155, v148
	ds_bpermute_b32 v151, v155, v149
	v_lshlrev_b32_e32 v143, 8, v143
	v_and_b32_e32 v143, 0xff00, v143
	v_and_b32_e32 v161, 0xff0000, v161
	v_perm_b32 v133, v162, v133, s65
	v_or3_b32 v133, v133, v143, v161
	global_store_dword v[146:147], v133, off offset:144
	s_and_saveexec_b64 s[42:43], s[16:17]
	s_cbranch_execz .LBB0_1162
	s_lshl_b32 s44, s26, 2
	v_lshlrev_b64 v[144:145], 6, v[144:145]
	s_ashr_i32 s45, s44, 31
	v_lshl_add_u64 v[144:145], v[144:145], 0, s[44:45]
	v_or_b32_e32 v144, s3, v144
	s_waitcnt lgkmcnt(0)
	v_pk_add_f32 v[146:147], v[148:149], v[150:151]
	v_lshl_add_u64 v[144:145], v[144:145], 3, s[8:9]
	global_store_dwordx2 v[144:145], v[146:147], off
.LBB0_1162:
	s_or_b64 exec, exec, s[42:43]
	v_or_b32_e32 v144, 32, v142
	v_ashrrev_i32_e32 v145, 31, v144
	v_lshlrev_b64 v[146:147], 12, v[144:145]
	v_lshl_add_u64 v[146:147], v[146:147], 0, v[140:141]
	v_lshlrev_b64 v[148:149], 1, v[146:147]
	s_waitcnt lgkmcnt(0)
	v_lshl_add_u64 v[150:151], s[0:1], 0, v[148:149]
	v_lshl_add_u64 v[146:147], s[10:11], 0, v[146:147]
	v_lshl_add_u64 v[148:149], s[6:7], 0, v[148:149]
	s_waitcnt vmcnt(39)
	v_mov_b32_e32 v162, v200
	v_mov_b32_e32 v163, v201
	v_lshlrev_b32_e32 v164, 16, v162
	v_and_b32_e32 v165, 0xffff0000, v162
	v_lshlrev_b32_e32 v162, 16, v163
	v_and_b32_e32 v163, 0xffff0000, v163
	v_pk_fma_f32 v[164:165], v[164:165], s[24:25], v[100:101] op_sel_hi:[1,0,1]
	v_pk_fma_f32 v[162:163], v[162:163], s[24:25], v[102:103] op_sel_hi:[1,0,1]
	v_mul_f32_e32 v143, 0x417e0000, v165
	v_mul_f32_e32 v133, 0x417e0000, v164
	v_mul_f32_e32 v161, 0x417e0000, v162
	v_mul_f32_e32 v168, 0x417e0000, v163
	v_med3_f32 v143, v143, s64, v160
	v_med3_f32 v133, v133, s64, v160
	v_med3_f32 v161, v161, s64, v160
	v_med3_f32 v168, v168, s64, v160
	v_rndne_f32_e32 v143, v143
	v_rndne_f32_e32 v133, v133
	v_rndne_f32_e32 v161, v161
	v_rndne_f32_e32 v168, v168
	v_cvt_i32_f32_e32 v143, v143
	v_cvt_i32_f32_e32 v133, v133
	v_cvt_i32_f32_sdwa v161, v161 dst_sel:WORD_1 dst_unused:UNUSED_PAD src0_sel:DWORD
	v_cvt_i32_f32_e32 v168, v168
	v_lshlrev_b32_e32 v143, 8, v143
	v_and_b32_e32 v143, 0xff00, v143
	v_and_b32_e32 v161, 0xff0000, v161
	v_perm_b32 v133, v168, v133, s65
	v_or3_b32 v133, v133, v143, v161
	v_cvt_pk_bf16_f32 v166, v164, v165
	v_cvt_pk_bf16_f32 v167, v162, v163
	global_store_dwordx2 v[148:149], v[166:167], off
	global_store_dword v[146:147], v133, off
	v_mul_f32_e32 v179, v164, v164
	v_mul_f32_e32 v181, v162, v162
	s_waitcnt vmcnt(40)
	v_mov_b32_e32 v166, v202
	v_mov_b32_e32 v167, v203
	v_lshlrev_b32_e32 v168, 16, v166
	v_and_b32_e32 v169, 0xffff0000, v166
	v_lshlrev_b32_e32 v166, 16, v167
	v_and_b32_e32 v167, 0xffff0000, v167
	v_pk_fma_f32 v[168:169], v[168:169], s[24:25], v[92:93] op_sel_hi:[1,0,1]
	v_pk_fma_f32 v[166:167], v[166:167], s[24:25], v[94:95] op_sel_hi:[1,0,1]
	v_mul_f32_e32 v143, 0x417e0000, v169
	v_mul_f32_e32 v133, 0x417e0000, v168
	v_mul_f32_e32 v161, 0x417e0000, v166
	v_mul_f32_e32 v172, 0x417e0000, v167
	v_med3_f32 v143, v143, s64, v160
	v_med3_f32 v133, v133, s64, v160
	v_med3_f32 v161, v161, s64, v160
	v_med3_f32 v172, v172, s64, v160
	v_rndne_f32_e32 v143, v143
	v_rndne_f32_e32 v133, v133
	v_rndne_f32_e32 v161, v161
	v_rndne_f32_e32 v172, v172
	v_cvt_i32_f32_e32 v143, v143
	v_cvt_i32_f32_e32 v133, v133
	v_cvt_i32_f32_sdwa v161, v161 dst_sel:WORD_1 dst_unused:UNUSED_PAD src0_sel:DWORD
	v_cvt_i32_f32_e32 v172, v172
	v_lshlrev_b32_e32 v143, 8, v143
	v_and_b32_e32 v143, 0xff00, v143
	v_and_b32_e32 v161, 0xff0000, v161
	v_perm_b32 v133, v172, v133, s65
	v_or3_b32 v133, v133, v143, v161
	v_cvt_pk_bf16_f32 v170, v168, v169
	v_cvt_pk_bf16_f32 v171, v166, v167
	global_store_dwordx2 v[148:149], v[170:171], off offset:32
	global_store_dword v[146:147], v133, off offset:16
	v_mul_f32_e32 v182, v166, v166
	v_mul_f32_e32 v177, v169, v169
	v_mov_b32_e32 v178, v168
	v_mov_b32_e32 v180, v166
	s_waitcnt vmcnt(41)
	v_mov_b32_e32 v170, v204
	v_mov_b32_e32 v171, v205
	v_lshlrev_b32_e32 v172, 16, v170
	v_and_b32_e32 v173, 0xffff0000, v170
	v_lshlrev_b32_e32 v170, 16, v171
	v_and_b32_e32 v171, 0xffff0000, v171
	v_pk_fma_f32 v[172:173], v[172:173], s[24:25], v[80:81] op_sel_hi:[1,0,1]
	v_pk_fma_f32 v[170:171], v[170:171], s[24:25], v[82:83] op_sel_hi:[1,0,1]
	v_mul_f32_e32 v143, 0x417e0000, v173
	v_mul_f32_e32 v133, 0x417e0000, v172
	v_mul_f32_e32 v161, 0x417e0000, v170
	v_mul_f32_e32 v176, 0x417e0000, v171
	v_med3_f32 v143, v143, s64, v160
	v_med3_f32 v133, v133, s64, v160
	v_med3_f32 v161, v161, s64, v160
	v_med3_f32 v176, v176, s64, v160
	v_rndne_f32_e32 v143, v143
	v_rndne_f32_e32 v133, v133
	v_rndne_f32_e32 v161, v161
	v_rndne_f32_e32 v176, v176
	v_cvt_i32_f32_e32 v143, v143
	v_cvt_i32_f32_e32 v133, v133
	v_cvt_i32_f32_sdwa v161, v161 dst_sel:WORD_1 dst_unused:UNUSED_PAD src0_sel:DWORD
	v_cvt_i32_f32_e32 v176, v176
	v_lshlrev_b32_e32 v143, 8, v143
	v_and_b32_e32 v143, 0xff00, v143
	v_and_b32_e32 v161, 0xff0000, v161
	v_perm_b32 v133, v176, v133, s65
	v_or3_b32 v133, v133, v143, v161
	v_cvt_pk_bf16_f32 v174, v172, v173
	v_cvt_pk_bf16_f32 v175, v170, v171
	global_store_dwordx2 v[148:149], v[174:175], off offset:256
	global_store_dword v[146:147], v133, off offset:128
	v_add_f32_e32 v174, v164, v165
	v_add_f32_e32 v176, v162, v163
	v_mul_f32_e32 v165, v165, v165
	v_mul_f32_e32 v163, v163, v163
	v_mul_f32_e32 v175, v168, v168
	v_mov_b32_e32 v164, v169
	v_mov_b32_e32 v162, v167
	v_pk_fma_f32 v[166:167], v[166:167], v[166:167], v[182:183] op_sel_hi:[1,1,0]
	v_pk_add_f32 v[164:165], v[178:179], v[164:165]
	v_pk_add_f32 v[162:163], v[180:181], v[162:163]
	v_pk_add_f32 v[168:169], v[174:175], v[176:177]
	v_mov_b32_e32 v133, v167
	v_pk_add_f32 v[162:163], v[164:165], v[162:163]
	v_pk_add_f32 v[164:165], v[168:169], v[132:133]
	v_mul_f32_e32 v167, v173, v173
	v_pk_add_f32 v[162:163], v[162:163], v[164:165]
	v_mul_f32_e32 v165, v172, v172
	v_mul_f32_e32 v169, v170, v170
	v_mul_f32_e32 v175, v171, v171
	v_mov_b32_e32 v164, v172
	v_mov_b32_e32 v166, v173
	v_mov_b32_e32 v168, v170
	v_mov_b32_e32 v174, v171
	v_pk_add_f32 v[164:165], v[164:165], v[166:167]
	v_pk_add_f32 v[166:167], v[168:169], v[174:175]
	s_nop 0
	v_pk_add_f32 v[164:165], v[164:165], v[166:167]
	s_nop 0
	v_pk_add_f32 v[162:163], v[162:163], v[164:165]
	s_waitcnt vmcnt(42)
	v_mov_b32_e32 v150, v206
	v_mov_b32_e32 v151, v207
	v_lshlrev_b32_e32 v164, 16, v150
	v_and_b32_e32 v165, 0xffff0000, v150
	v_lshlrev_b32_e32 v150, 16, v151
	v_and_b32_e32 v151, 0xffff0000, v151
	v_pk_fma_f32 v[150:151], v[150:151], s[24:25], v[74:75] op_sel_hi:[1,0,1]
	v_pk_fma_f32 v[164:165], v[164:165], s[24:25], v[72:73] op_sel_hi:[1,0,1]
	v_mul_f32_e32 v173, v150, v150
	v_mul_f32_e32 v169, v164, v164
	v_mul_f32_e32 v171, v165, v165
	v_mul_f32_e32 v175, v151, v151
	v_mov_b32_e32 v168, v164
	v_mov_b32_e32 v170, v165
	v_mov_b32_e32 v172, v150
	v_mov_b32_e32 v174, v151
	v_cvt_pk_bf16_f32 v166, v164, v165
	v_cvt_pk_bf16_f32 v167, v150, v151
	v_mul_f32_e32 v161, 0x417e0000, v150
	v_mul_f32_e32 v176, 0x417e0000, v151
	global_store_dwordx2 v[148:149], v[166:167], off offset:288
	v_pk_add_f32 v[148:149], v[168:169], v[170:171]
	v_pk_add_f32 v[150:151], v[172:173], v[174:175]
	v_mul_f32_e32 v143, 0x417e0000, v165
	v_pk_add_f32 v[148:149], v[148:149], v[150:151]
	v_mul_f32_e32 v133, 0x417e0000, v164
	v_pk_add_f32 v[148:149], v[162:163], v[148:149]
	ds_swizzle_b32 v150, v148 offset:swizzle(SWAP,16)
	ds_swizzle_b32 v151, v149 offset:swizzle(SWAP,16)
	v_med3_f32 v143, v143, s64, v160
	v_med3_f32 v133, v133, s64, v160
	v_med3_f32 v161, v161, s64, v160
	v_med3_f32 v164, v176, s64, v160
	v_rndne_f32_e32 v143, v143
	v_rndne_f32_e32 v133, v133
	v_rndne_f32_e32 v161, v161
	v_rndne_f32_e32 v164, v164
	v_cvt_i32_f32_e32 v143, v143
	v_cvt_i32_f32_e32 v133, v133
	v_cvt_i32_f32_sdwa v161, v161 dst_sel:WORD_1 dst_unused:UNUSED_PAD src0_sel:DWORD
	v_cvt_i32_f32_e32 v162, v164
	s_waitcnt lgkmcnt(0)
	v_pk_add_f32 v[148:149], v[148:149], v[150:151]
	ds_bpermute_b32 v150, v155, v148
	ds_bpermute_b32 v151, v155, v149
	v_lshlrev_b32_e32 v143, 8, v143
	v_and_b32_e32 v143, 0xff00, v143
	v_and_b32_e32 v161, 0xff0000, v161
	v_perm_b32 v133, v162, v133, s65
	v_or3_b32 v133, v133, v143, v161
	global_store_dword v[146:147], v133, off offset:144
	s_and_saveexec_b64 s[42:43], s[16:17]
	s_cbranch_execz .LBB0_1164
	s_lshl_b32 s44, s26, 2
	v_lshlrev_b64 v[144:145], 6, v[144:145]
	s_ashr_i32 s45, s44, 31
	v_lshl_add_u64 v[144:145], v[144:145], 0, s[44:45]
	v_or_b32_e32 v144, s3, v144
	s_waitcnt lgkmcnt(0)
	v_pk_add_f32 v[146:147], v[148:149], v[150:151]
	v_lshl_add_u64 v[144:145], v[144:145], 3, s[8:9]
	global_store_dwordx2 v[144:145], v[146:147], off
.LBB0_1164:
	s_or_b64 exec, exec, s[42:43]
	v_or_b32_e32 v144, 48, v142
	v_ashrrev_i32_e32 v145, 31, v144
	v_lshlrev_b64 v[146:147], 12, v[144:145]
	v_lshl_add_u64 v[146:147], v[146:147], 0, v[140:141]
	v_lshlrev_b64 v[148:149], 1, v[146:147]
	s_waitcnt lgkmcnt(0)
	v_lshl_add_u64 v[150:151], s[0:1], 0, v[148:149]
	v_lshl_add_u64 v[146:147], s[10:11], 0, v[146:147]
	v_lshl_add_u64 v[148:149], s[6:7], 0, v[148:149]
	s_waitcnt vmcnt(43)
	v_mov_b32_e32 v162, v208
	v_mov_b32_e32 v163, v209
	v_lshlrev_b32_e32 v164, 16, v162
	v_and_b32_e32 v165, 0xffff0000, v162
	v_lshlrev_b32_e32 v162, 16, v163
	v_and_b32_e32 v163, 0xffff0000, v163
	v_pk_fma_f32 v[164:165], v[164:165], s[24:25], v[84:85] op_sel_hi:[1,0,1]
	v_pk_fma_f32 v[162:163], v[162:163], s[24:25], v[86:87] op_sel_hi:[1,0,1]
	v_mul_f32_e32 v143, 0x417e0000, v165
	v_mul_f32_e32 v133, 0x417e0000, v164
	v_mul_f32_e32 v161, 0x417e0000, v162
	v_mul_f32_e32 v168, 0x417e0000, v163
	v_med3_f32 v143, v143, s64, v160
	v_med3_f32 v133, v133, s64, v160
	v_med3_f32 v161, v161, s64, v160
	v_med3_f32 v168, v168, s64, v160
	v_rndne_f32_e32 v143, v143
	v_rndne_f32_e32 v133, v133
	v_rndne_f32_e32 v161, v161
	v_rndne_f32_e32 v168, v168
	v_cvt_i32_f32_e32 v143, v143
	v_cvt_i32_f32_e32 v133, v133
	v_cvt_i32_f32_sdwa v161, v161 dst_sel:WORD_1 dst_unused:UNUSED_PAD src0_sel:DWORD
	v_cvt_i32_f32_e32 v168, v168
	v_lshlrev_b32_e32 v143, 8, v143
	v_and_b32_e32 v143, 0xff00, v143
	v_and_b32_e32 v161, 0xff0000, v161
	v_perm_b32 v133, v168, v133, s65
	v_or3_b32 v133, v133, v143, v161
	v_cvt_pk_bf16_f32 v166, v164, v165
	v_cvt_pk_bf16_f32 v167, v162, v163
	global_store_dwordx2 v[148:149], v[166:167], off
	global_store_dword v[146:147], v133, off
	v_mul_f32_e32 v179, v164, v164
	v_mul_f32_e32 v181, v162, v162
	s_waitcnt vmcnt(44)
	v_mov_b32_e32 v166, v210
	v_mov_b32_e32 v167, v211
	v_lshlrev_b32_e32 v168, 16, v166
	v_and_b32_e32 v169, 0xffff0000, v166
	v_lshlrev_b32_e32 v166, 16, v167
	v_and_b32_e32 v167, 0xffff0000, v167
	v_pk_fma_f32 v[168:169], v[168:169], s[24:25], v[76:77] op_sel_hi:[1,0,1]
	v_pk_fma_f32 v[166:167], v[166:167], s[24:25], v[78:79] op_sel_hi:[1,0,1]
	v_mul_f32_e32 v143, 0x417e0000, v169
	v_mul_f32_e32 v133, 0x417e0000, v168
	v_mul_f32_e32 v161, 0x417e0000, v166
	v_mul_f32_e32 v172, 0x417e0000, v167
	v_med3_f32 v143, v143, s64, v160
	v_med3_f32 v133, v133, s64, v160
	v_med3_f32 v161, v161, s64, v160
	v_med3_f32 v172, v172, s64, v160
	v_rndne_f32_e32 v143, v143
	v_rndne_f32_e32 v133, v133
	v_rndne_f32_e32 v161, v161
	v_rndne_f32_e32 v172, v172
	v_cvt_i32_f32_e32 v143, v143
	v_cvt_i32_f32_e32 v133, v133
	v_cvt_i32_f32_sdwa v161, v161 dst_sel:WORD_1 dst_unused:UNUSED_PAD src0_sel:DWORD
	v_cvt_i32_f32_e32 v172, v172
	v_lshlrev_b32_e32 v143, 8, v143
	v_and_b32_e32 v143, 0xff00, v143
	v_and_b32_e32 v161, 0xff0000, v161
	v_perm_b32 v133, v172, v133, s65
	v_or3_b32 v133, v133, v143, v161
	v_cvt_pk_bf16_f32 v170, v168, v169
	v_cvt_pk_bf16_f32 v171, v166, v167
	global_store_dwordx2 v[148:149], v[170:171], off offset:32
	global_store_dword v[146:147], v133, off offset:16
	v_mul_f32_e32 v182, v166, v166
	v_mul_f32_e32 v177, v169, v169
	v_mov_b32_e32 v178, v168
	v_mov_b32_e32 v180, v166
	s_waitcnt vmcnt(45)
	v_mov_b32_e32 v170, v212
	v_mov_b32_e32 v171, v213
	v_lshlrev_b32_e32 v172, 16, v170
	v_and_b32_e32 v173, 0xffff0000, v170
	v_lshlrev_b32_e32 v170, 16, v171
	v_and_b32_e32 v171, 0xffff0000, v171
	v_pk_fma_f32 v[172:173], v[172:173], s[24:25], v[68:69] op_sel_hi:[1,0,1]
	v_pk_fma_f32 v[170:171], v[170:171], s[24:25], v[70:71] op_sel_hi:[1,0,1]
	v_mul_f32_e32 v143, 0x417e0000, v173
	v_mul_f32_e32 v133, 0x417e0000, v172
	v_mul_f32_e32 v161, 0x417e0000, v170
	v_mul_f32_e32 v176, 0x417e0000, v171
	v_med3_f32 v143, v143, s64, v160
	v_med3_f32 v133, v133, s64, v160
	v_med3_f32 v161, v161, s64, v160
	v_med3_f32 v176, v176, s64, v160
	v_rndne_f32_e32 v143, v143
	v_rndne_f32_e32 v133, v133
	v_rndne_f32_e32 v161, v161
	v_rndne_f32_e32 v176, v176
	v_cvt_i32_f32_e32 v143, v143
	v_cvt_i32_f32_e32 v133, v133
	v_cvt_i32_f32_sdwa v161, v161 dst_sel:WORD_1 dst_unused:UNUSED_PAD src0_sel:DWORD
	v_cvt_i32_f32_e32 v176, v176
	v_lshlrev_b32_e32 v143, 8, v143
	v_and_b32_e32 v143, 0xff00, v143
	v_and_b32_e32 v161, 0xff0000, v161
	v_perm_b32 v133, v176, v133, s65
	v_or3_b32 v133, v133, v143, v161
	v_cvt_pk_bf16_f32 v174, v172, v173
	v_cvt_pk_bf16_f32 v175, v170, v171
	global_store_dwordx2 v[148:149], v[174:175], off offset:256
	global_store_dword v[146:147], v133, off offset:128
	v_add_f32_e32 v174, v164, v165
	v_add_f32_e32 v176, v162, v163
	v_mul_f32_e32 v165, v165, v165
	v_mul_f32_e32 v163, v163, v163
	v_mul_f32_e32 v175, v168, v168
	v_mov_b32_e32 v164, v169
	v_mov_b32_e32 v162, v167
	v_pk_fma_f32 v[166:167], v[166:167], v[166:167], v[182:183] op_sel_hi:[1,1,0]
	v_pk_add_f32 v[164:165], v[178:179], v[164:165]
	v_pk_add_f32 v[162:163], v[180:181], v[162:163]
	v_pk_add_f32 v[168:169], v[174:175], v[176:177]
	v_mov_b32_e32 v133, v167
	v_pk_add_f32 v[162:163], v[164:165], v[162:163]
	v_pk_add_f32 v[164:165], v[168:169], v[132:133]
	v_mul_f32_e32 v167, v173, v173
	v_pk_add_f32 v[162:163], v[162:163], v[164:165]
	v_mul_f32_e32 v165, v172, v172
	v_mul_f32_e32 v169, v170, v170
	v_mul_f32_e32 v175, v171, v171
	v_mov_b32_e32 v164, v172
	v_mov_b32_e32 v166, v173
	v_mov_b32_e32 v168, v170
	v_mov_b32_e32 v174, v171
	v_pk_add_f32 v[164:165], v[164:165], v[166:167]
	v_pk_add_f32 v[166:167], v[168:169], v[174:175]
	s_nop 0
	v_pk_add_f32 v[164:165], v[164:165], v[166:167]
	s_nop 0
	v_pk_add_f32 v[162:163], v[162:163], v[164:165]
	s_waitcnt vmcnt(46)
	v_mov_b32_e32 v150, v214
	v_mov_b32_e32 v151, v215
	v_lshlrev_b32_e32 v164, 16, v150
	v_and_b32_e32 v165, 0xffff0000, v150
	v_lshlrev_b32_e32 v150, 16, v151
	v_and_b32_e32 v151, 0xffff0000, v151
	v_pk_fma_f32 v[150:151], v[150:151], s[24:25], v[66:67] op_sel_hi:[1,0,1]
	v_pk_fma_f32 v[164:165], v[164:165], s[24:25], v[64:65] op_sel_hi:[1,0,1]
	v_mul_f32_e32 v173, v150, v150
	v_mul_f32_e32 v169, v164, v164
	v_mul_f32_e32 v171, v165, v165
	v_mul_f32_e32 v175, v151, v151
	v_mov_b32_e32 v168, v164
	v_mov_b32_e32 v170, v165
	v_mov_b32_e32 v172, v150
	v_mov_b32_e32 v174, v151
	v_cvt_pk_bf16_f32 v166, v164, v165
	v_cvt_pk_bf16_f32 v167, v150, v151
	v_mul_f32_e32 v161, 0x417e0000, v150
	v_mul_f32_e32 v176, 0x417e0000, v151
	global_store_dwordx2 v[148:149], v[166:167], off offset:288
	v_pk_add_f32 v[148:149], v[168:169], v[170:171]
	v_pk_add_f32 v[150:151], v[172:173], v[174:175]
	v_mul_f32_e32 v143, 0x417e0000, v165
	v_pk_add_f32 v[148:149], v[148:149], v[150:151]
	v_mul_f32_e32 v133, 0x417e0000, v164
	v_pk_add_f32 v[148:149], v[162:163], v[148:149]
	ds_swizzle_b32 v150, v148 offset:swizzle(SWAP,16)
	ds_swizzle_b32 v151, v149 offset:swizzle(SWAP,16)
	v_med3_f32 v143, v143, s64, v160
	v_med3_f32 v133, v133, s64, v160
	v_med3_f32 v161, v161, s64, v160
	v_med3_f32 v164, v176, s64, v160
	v_rndne_f32_e32 v143, v143
	v_rndne_f32_e32 v133, v133
	v_rndne_f32_e32 v161, v161
	v_rndne_f32_e32 v164, v164
	v_cvt_i32_f32_e32 v143, v143
	v_cvt_i32_f32_e32 v133, v133
	v_cvt_i32_f32_sdwa v161, v161 dst_sel:WORD_1 dst_unused:UNUSED_PAD src0_sel:DWORD
	v_cvt_i32_f32_e32 v162, v164
	s_waitcnt lgkmcnt(0)
	v_pk_add_f32 v[148:149], v[148:149], v[150:151]
	ds_bpermute_b32 v150, v155, v148
	ds_bpermute_b32 v151, v155, v149
	v_lshlrev_b32_e32 v143, 8, v143
	v_and_b32_e32 v143, 0xff00, v143
	v_and_b32_e32 v161, 0xff0000, v161
	v_perm_b32 v133, v162, v133, s65
	v_or3_b32 v133, v133, v143, v161
	global_store_dword v[146:147], v133, off offset:144
	s_and_saveexec_b64 s[42:43], s[16:17]
	s_cbranch_execz .LBB0_1166
	s_lshl_b32 s44, s26, 2
	v_lshlrev_b64 v[144:145], 6, v[144:145]
	s_ashr_i32 s45, s44, 31
	v_lshl_add_u64 v[144:145], v[144:145], 0, s[44:45]
	v_or_b32_e32 v144, s3, v144
	s_waitcnt lgkmcnt(0)
	v_pk_add_f32 v[146:147], v[148:149], v[150:151]
	v_lshl_add_u64 v[144:145], v[144:145], 3, s[8:9]
	global_store_dwordx2 v[144:145], v[146:147], off
.LBB0_1166:
	s_or_b64 exec, exec, s[42:43]
	v_add_u32_e32 v144, 0x80, v142
	v_ashrrev_i32_e32 v145, 31, v144
	v_lshlrev_b64 v[146:147], 12, v[144:145]
	v_lshl_add_u64 v[146:147], v[146:147], 0, v[140:141]
	v_lshlrev_b64 v[148:149], 1, v[146:147]
	s_waitcnt lgkmcnt(0)
	v_lshl_add_u64 v[150:151], s[0:1], 0, v[148:149]
	v_lshl_add_u64 v[146:147], s[10:11], 0, v[146:147]
	v_lshl_add_u64 v[148:149], s[6:7], 0, v[148:149]
	s_waitcnt vmcnt(47)
	v_mov_b32_e32 v162, v216
	v_mov_b32_e32 v163, v217
	v_lshlrev_b32_e32 v164, 16, v162
	v_and_b32_e32 v165, 0xffff0000, v162
	v_lshlrev_b32_e32 v162, 16, v163
	v_and_b32_e32 v163, 0xffff0000, v163
	v_pk_fma_f32 v[164:165], v[164:165], s[24:25], v[60:61] op_sel_hi:[1,0,1]
	v_pk_fma_f32 v[162:163], v[162:163], s[24:25], v[62:63] op_sel_hi:[1,0,1]
	v_mul_f32_e32 v143, 0x417e0000, v165
	v_mul_f32_e32 v133, 0x417e0000, v164
	v_mul_f32_e32 v161, 0x417e0000, v162
	v_mul_f32_e32 v168, 0x417e0000, v163
	v_med3_f32 v143, v143, s64, v160
	v_med3_f32 v133, v133, s64, v160
	v_med3_f32 v161, v161, s64, v160
	v_med3_f32 v168, v168, s64, v160
	v_rndne_f32_e32 v143, v143
	v_rndne_f32_e32 v133, v133
	v_rndne_f32_e32 v161, v161
	v_rndne_f32_e32 v168, v168
	v_cvt_i32_f32_e32 v143, v143
	v_cvt_i32_f32_e32 v133, v133
	v_cvt_i32_f32_sdwa v161, v161 dst_sel:WORD_1 dst_unused:UNUSED_PAD src0_sel:DWORD
	v_cvt_i32_f32_e32 v168, v168
	v_lshlrev_b32_e32 v143, 8, v143
	v_and_b32_e32 v143, 0xff00, v143
	v_and_b32_e32 v161, 0xff0000, v161
	v_perm_b32 v133, v168, v133, s65
	v_or3_b32 v133, v133, v143, v161
	v_cvt_pk_bf16_f32 v166, v164, v165
	v_cvt_pk_bf16_f32 v167, v162, v163
	global_store_dwordx2 v[148:149], v[166:167], off
	global_store_dword v[146:147], v133, off
	v_mul_f32_e32 v179, v164, v164
	v_mul_f32_e32 v181, v162, v162
	s_waitcnt vmcnt(48)
	v_mov_b32_e32 v166, v218
	v_mov_b32_e32 v167, v219
	v_lshlrev_b32_e32 v168, 16, v166
	v_and_b32_e32 v169, 0xffff0000, v166
	v_lshlrev_b32_e32 v166, 16, v167
	v_and_b32_e32 v167, 0xffff0000, v167
	v_pk_fma_f32 v[168:169], v[168:169], s[24:25], v[56:57] op_sel_hi:[1,0,1]
	v_pk_fma_f32 v[166:167], v[166:167], s[24:25], v[58:59] op_sel_hi:[1,0,1]
	v_mul_f32_e32 v143, 0x417e0000, v169
	v_mul_f32_e32 v133, 0x417e0000, v168
	v_mul_f32_e32 v161, 0x417e0000, v166
	v_mul_f32_e32 v172, 0x417e0000, v167
	v_med3_f32 v143, v143, s64, v160
	v_med3_f32 v133, v133, s64, v160
	v_med3_f32 v161, v161, s64, v160
	v_med3_f32 v172, v172, s64, v160
	v_rndne_f32_e32 v143, v143
	v_rndne_f32_e32 v133, v133
	v_rndne_f32_e32 v161, v161
	v_rndne_f32_e32 v172, v172
	v_cvt_i32_f32_e32 v143, v143
	v_cvt_i32_f32_e32 v133, v133
	v_cvt_i32_f32_sdwa v161, v161 dst_sel:WORD_1 dst_unused:UNUSED_PAD src0_sel:DWORD
	v_cvt_i32_f32_e32 v172, v172
	v_lshlrev_b32_e32 v143, 8, v143
	v_and_b32_e32 v143, 0xff00, v143
	v_and_b32_e32 v161, 0xff0000, v161
	v_perm_b32 v133, v172, v133, s65
	v_or3_b32 v133, v133, v143, v161
	v_cvt_pk_bf16_f32 v170, v168, v169
	v_cvt_pk_bf16_f32 v171, v166, v167
	global_store_dwordx2 v[148:149], v[170:171], off offset:32
	global_store_dword v[146:147], v133, off offset:16
	v_mul_f32_e32 v182, v166, v166
	v_mul_f32_e32 v177, v169, v169
	v_mov_b32_e32 v178, v168
	v_mov_b32_e32 v180, v166
	s_waitcnt vmcnt(49)
	v_mov_b32_e32 v170, v220
	v_mov_b32_e32 v171, v221
	v_lshlrev_b32_e32 v172, 16, v170
	v_and_b32_e32 v173, 0xffff0000, v170
	v_lshlrev_b32_e32 v170, 16, v171
	v_and_b32_e32 v171, 0xffff0000, v171
	v_pk_fma_f32 v[172:173], v[172:173], s[24:25], v[48:49] op_sel_hi:[1,0,1]
	v_pk_fma_f32 v[170:171], v[170:171], s[24:25], v[50:51] op_sel_hi:[1,0,1]
	v_mul_f32_e32 v143, 0x417e0000, v173
	v_mul_f32_e32 v133, 0x417e0000, v172
	v_mul_f32_e32 v161, 0x417e0000, v170
	v_mul_f32_e32 v176, 0x417e0000, v171
	v_med3_f32 v143, v143, s64, v160
	v_med3_f32 v133, v133, s64, v160
	v_med3_f32 v161, v161, s64, v160
	v_med3_f32 v176, v176, s64, v160
	v_rndne_f32_e32 v143, v143
	v_rndne_f32_e32 v133, v133
	v_rndne_f32_e32 v161, v161
	v_rndne_f32_e32 v176, v176
	v_cvt_i32_f32_e32 v143, v143
	v_cvt_i32_f32_e32 v133, v133
	v_cvt_i32_f32_sdwa v161, v161 dst_sel:WORD_1 dst_unused:UNUSED_PAD src0_sel:DWORD
	v_cvt_i32_f32_e32 v176, v176
	v_lshlrev_b32_e32 v143, 8, v143
	v_and_b32_e32 v143, 0xff00, v143
	v_and_b32_e32 v161, 0xff0000, v161
	v_perm_b32 v133, v176, v133, s65
	v_or3_b32 v133, v133, v143, v161
	v_cvt_pk_bf16_f32 v174, v172, v173
	v_cvt_pk_bf16_f32 v175, v170, v171
	global_store_dwordx2 v[148:149], v[174:175], off offset:256
	global_store_dword v[146:147], v133, off offset:128
	v_add_f32_e32 v174, v164, v165
	v_add_f32_e32 v176, v162, v163
	v_mul_f32_e32 v165, v165, v165
	v_mul_f32_e32 v163, v163, v163
	v_mul_f32_e32 v175, v168, v168
	v_mov_b32_e32 v164, v169
	v_mov_b32_e32 v162, v167
	v_pk_fma_f32 v[166:167], v[166:167], v[166:167], v[182:183] op_sel_hi:[1,1,0]
	v_pk_add_f32 v[164:165], v[178:179], v[164:165]
	v_pk_add_f32 v[162:163], v[180:181], v[162:163]
	v_pk_add_f32 v[168:169], v[174:175], v[176:177]
	v_mov_b32_e32 v133, v167
	v_pk_add_f32 v[162:163], v[164:165], v[162:163]
	v_pk_add_f32 v[164:165], v[168:169], v[132:133]
	v_mul_f32_e32 v167, v173, v173
	v_pk_add_f32 v[162:163], v[162:163], v[164:165]
	v_mul_f32_e32 v165, v172, v172
	v_mul_f32_e32 v169, v170, v170
	v_mul_f32_e32 v175, v171, v171
	v_mov_b32_e32 v164, v172
	v_mov_b32_e32 v166, v173
	v_mov_b32_e32 v168, v170
	v_mov_b32_e32 v174, v171
	v_pk_add_f32 v[164:165], v[164:165], v[166:167]
	v_pk_add_f32 v[166:167], v[168:169], v[174:175]
	s_nop 0
	v_pk_add_f32 v[164:165], v[164:165], v[166:167]
	s_nop 0
	v_pk_add_f32 v[162:163], v[162:163], v[164:165]
	s_waitcnt vmcnt(50)
	v_mov_b32_e32 v150, v222
	v_mov_b32_e32 v151, v223
	v_lshlrev_b32_e32 v164, 16, v150
	v_and_b32_e32 v165, 0xffff0000, v150
	v_lshlrev_b32_e32 v150, 16, v151
	v_and_b32_e32 v151, 0xffff0000, v151
	v_pk_fma_f32 v[150:151], v[150:151], s[24:25], v[46:47] op_sel_hi:[1,0,1]
	v_pk_fma_f32 v[164:165], v[164:165], s[24:25], v[44:45] op_sel_hi:[1,0,1]
	v_mul_f32_e32 v173, v150, v150
	v_mul_f32_e32 v169, v164, v164
	v_mul_f32_e32 v171, v165, v165
	v_mul_f32_e32 v175, v151, v151
	v_mov_b32_e32 v168, v164
	v_mov_b32_e32 v170, v165
	v_mov_b32_e32 v172, v150
	v_mov_b32_e32 v174, v151
	v_cvt_pk_bf16_f32 v166, v164, v165
	v_cvt_pk_bf16_f32 v167, v150, v151
	v_mul_f32_e32 v161, 0x417e0000, v150
	v_mul_f32_e32 v176, 0x417e0000, v151
	global_store_dwordx2 v[148:149], v[166:167], off offset:288
	v_pk_add_f32 v[148:149], v[168:169], v[170:171]
	v_pk_add_f32 v[150:151], v[172:173], v[174:175]
	v_mul_f32_e32 v143, 0x417e0000, v165
	v_pk_add_f32 v[148:149], v[148:149], v[150:151]
	v_mul_f32_e32 v133, 0x417e0000, v164
	v_pk_add_f32 v[148:149], v[162:163], v[148:149]
	ds_swizzle_b32 v150, v148 offset:swizzle(SWAP,16)
	ds_swizzle_b32 v151, v149 offset:swizzle(SWAP,16)
	v_med3_f32 v143, v143, s64, v160
	v_med3_f32 v133, v133, s64, v160
	v_med3_f32 v161, v161, s64, v160
	v_med3_f32 v164, v176, s64, v160
	v_rndne_f32_e32 v143, v143
	v_rndne_f32_e32 v133, v133
	v_rndne_f32_e32 v161, v161
	v_rndne_f32_e32 v164, v164
	v_cvt_i32_f32_e32 v143, v143
	v_cvt_i32_f32_e32 v133, v133
	v_cvt_i32_f32_sdwa v161, v161 dst_sel:WORD_1 dst_unused:UNUSED_PAD src0_sel:DWORD
	v_cvt_i32_f32_e32 v162, v164
	s_waitcnt lgkmcnt(0)
	v_pk_add_f32 v[148:149], v[148:149], v[150:151]
	ds_bpermute_b32 v150, v155, v148
	ds_bpermute_b32 v151, v155, v149
	v_lshlrev_b32_e32 v143, 8, v143
	v_and_b32_e32 v143, 0xff00, v143
	v_and_b32_e32 v161, 0xff0000, v161
	v_perm_b32 v133, v162, v133, s65
	v_or3_b32 v133, v133, v143, v161
	global_store_dword v[146:147], v133, off offset:144
	s_and_saveexec_b64 s[42:43], s[16:17]
	s_cbranch_execz .LBB0_1168
	s_lshl_b32 s44, s26, 2
	v_lshlrev_b64 v[144:145], 6, v[144:145]
	s_ashr_i32 s45, s44, 31
	v_lshl_add_u64 v[144:145], v[144:145], 0, s[44:45]
	v_or_b32_e32 v144, s3, v144
	s_waitcnt lgkmcnt(0)
	v_pk_add_f32 v[146:147], v[148:149], v[150:151]
	v_lshl_add_u64 v[144:145], v[144:145], 3, s[8:9]
	global_store_dwordx2 v[144:145], v[146:147], off
.LBB0_1168:
	s_or_b64 exec, exec, s[42:43]
	v_add_u32_e32 v144, 0x90, v142
	v_ashrrev_i32_e32 v145, 31, v144
	v_lshlrev_b64 v[146:147], 12, v[144:145]
	v_lshl_add_u64 v[146:147], v[146:147], 0, v[140:141]
	v_lshlrev_b64 v[148:149], 1, v[146:147]
	s_waitcnt lgkmcnt(0)
	v_lshl_add_u64 v[150:151], s[0:1], 0, v[148:149]
	v_lshl_add_u64 v[146:147], s[10:11], 0, v[146:147]
	v_lshl_add_u64 v[148:149], s[6:7], 0, v[148:149]
	s_waitcnt vmcnt(51)
	v_mov_b32_e32 v162, v224
	v_mov_b32_e32 v163, v225
	v_lshlrev_b32_e32 v164, 16, v162
	v_and_b32_e32 v165, 0xffff0000, v162
	v_lshlrev_b32_e32 v162, 16, v163
	v_and_b32_e32 v163, 0xffff0000, v163
	v_pk_fma_f32 v[164:165], v[164:165], s[24:25], v[52:53] op_sel_hi:[1,0,1]
	v_pk_fma_f32 v[162:163], v[162:163], s[24:25], v[54:55] op_sel_hi:[1,0,1]
	v_mul_f32_e32 v143, 0x417e0000, v165
	v_mul_f32_e32 v133, 0x417e0000, v164
	v_mul_f32_e32 v161, 0x417e0000, v162
	v_mul_f32_e32 v168, 0x417e0000, v163
	v_med3_f32 v143, v143, s64, v160
	v_med3_f32 v133, v133, s64, v160
	v_med3_f32 v161, v161, s64, v160
	v_med3_f32 v168, v168, s64, v160
	v_rndne_f32_e32 v143, v143
	v_rndne_f32_e32 v133, v133
	v_rndne_f32_e32 v161, v161
	v_rndne_f32_e32 v168, v168
	v_cvt_i32_f32_e32 v143, v143
	v_cvt_i32_f32_e32 v133, v133
	v_cvt_i32_f32_sdwa v161, v161 dst_sel:WORD_1 dst_unused:UNUSED_PAD src0_sel:DWORD
	v_cvt_i32_f32_e32 v168, v168
	v_lshlrev_b32_e32 v143, 8, v143
	v_and_b32_e32 v143, 0xff00, v143
	v_and_b32_e32 v161, 0xff0000, v161
	v_perm_b32 v133, v168, v133, s65
	v_or3_b32 v133, v133, v143, v161
	v_cvt_pk_bf16_f32 v166, v164, v165
	v_cvt_pk_bf16_f32 v167, v162, v163
	global_store_dwordx2 v[148:149], v[166:167], off
	global_store_dword v[146:147], v133, off
	v_mul_f32_e32 v179, v164, v164
	v_mul_f32_e32 v181, v162, v162
	s_waitcnt vmcnt(52)
	v_mov_b32_e32 v166, v226
	v_mov_b32_e32 v167, v227
	v_lshlrev_b32_e32 v168, 16, v166
	v_and_b32_e32 v169, 0xffff0000, v166
	v_lshlrev_b32_e32 v166, 16, v167
	v_and_b32_e32 v167, 0xffff0000, v167
	v_pk_fma_f32 v[168:169], v[168:169], s[24:25], v[40:41] op_sel_hi:[1,0,1]
	v_pk_fma_f32 v[166:167], v[166:167], s[24:25], v[42:43] op_sel_hi:[1,0,1]
	v_mul_f32_e32 v143, 0x417e0000, v169
	v_mul_f32_e32 v133, 0x417e0000, v168
	v_mul_f32_e32 v161, 0x417e0000, v166
	v_mul_f32_e32 v172, 0x417e0000, v167
	v_med3_f32 v143, v143, s64, v160
	v_med3_f32 v133, v133, s64, v160
	v_med3_f32 v161, v161, s64, v160
	v_med3_f32 v172, v172, s64, v160
	v_rndne_f32_e32 v143, v143
	v_rndne_f32_e32 v133, v133
	v_rndne_f32_e32 v161, v161
	v_rndne_f32_e32 v172, v172
	v_cvt_i32_f32_e32 v143, v143
	v_cvt_i32_f32_e32 v133, v133
	v_cvt_i32_f32_sdwa v161, v161 dst_sel:WORD_1 dst_unused:UNUSED_PAD src0_sel:DWORD
	v_cvt_i32_f32_e32 v172, v172
	v_lshlrev_b32_e32 v143, 8, v143
	v_and_b32_e32 v143, 0xff00, v143
	v_and_b32_e32 v161, 0xff0000, v161
	v_perm_b32 v133, v172, v133, s65
	v_or3_b32 v133, v133, v143, v161
	v_cvt_pk_bf16_f32 v170, v168, v169
	v_cvt_pk_bf16_f32 v171, v166, v167
	global_store_dwordx2 v[148:149], v[170:171], off offset:32
	global_store_dword v[146:147], v133, off offset:16
	v_mul_f32_e32 v182, v166, v166
	v_mul_f32_e32 v177, v169, v169
	v_mov_b32_e32 v178, v168
	v_mov_b32_e32 v180, v166
	s_waitcnt vmcnt(53)
	v_mov_b32_e32 v170, v228
	v_mov_b32_e32 v171, v229
	v_lshlrev_b32_e32 v172, 16, v170
	v_and_b32_e32 v173, 0xffff0000, v170
	v_lshlrev_b32_e32 v170, 16, v171
	v_and_b32_e32 v171, 0xffff0000, v171
	v_pk_fma_f32 v[172:173], v[172:173], s[24:25], v[32:33] op_sel_hi:[1,0,1]
	v_pk_fma_f32 v[170:171], v[170:171], s[24:25], v[34:35] op_sel_hi:[1,0,1]
	v_mul_f32_e32 v143, 0x417e0000, v173
	v_mul_f32_e32 v133, 0x417e0000, v172
	v_mul_f32_e32 v161, 0x417e0000, v170
	v_mul_f32_e32 v176, 0x417e0000, v171
	v_med3_f32 v143, v143, s64, v160
	v_med3_f32 v133, v133, s64, v160
	v_med3_f32 v161, v161, s64, v160
	v_med3_f32 v176, v176, s64, v160
	v_rndne_f32_e32 v143, v143
	v_rndne_f32_e32 v133, v133
	v_rndne_f32_e32 v161, v161
	v_rndne_f32_e32 v176, v176
	v_cvt_i32_f32_e32 v143, v143
	v_cvt_i32_f32_e32 v133, v133
	v_cvt_i32_f32_sdwa v161, v161 dst_sel:WORD_1 dst_unused:UNUSED_PAD src0_sel:DWORD
	v_cvt_i32_f32_e32 v176, v176
	v_lshlrev_b32_e32 v143, 8, v143
	v_and_b32_e32 v143, 0xff00, v143
	v_and_b32_e32 v161, 0xff0000, v161
	v_perm_b32 v133, v176, v133, s65
	v_or3_b32 v133, v133, v143, v161
	v_cvt_pk_bf16_f32 v174, v172, v173
	v_cvt_pk_bf16_f32 v175, v170, v171
	global_store_dwordx2 v[148:149], v[174:175], off offset:256
	global_store_dword v[146:147], v133, off offset:128
	v_add_f32_e32 v174, v164, v165
	v_add_f32_e32 v176, v162, v163
	v_mul_f32_e32 v165, v165, v165
	v_mul_f32_e32 v163, v163, v163
	v_mul_f32_e32 v175, v168, v168
	v_mov_b32_e32 v164, v169
	v_mov_b32_e32 v162, v167
	v_pk_fma_f32 v[166:167], v[166:167], v[166:167], v[182:183] op_sel_hi:[1,1,0]
	v_pk_add_f32 v[164:165], v[178:179], v[164:165]
	v_pk_add_f32 v[162:163], v[180:181], v[162:163]
	v_pk_add_f32 v[168:169], v[174:175], v[176:177]
	v_mov_b32_e32 v133, v167
	v_pk_add_f32 v[162:163], v[164:165], v[162:163]
	v_pk_add_f32 v[164:165], v[168:169], v[132:133]
	v_mul_f32_e32 v167, v173, v173
	v_pk_add_f32 v[162:163], v[162:163], v[164:165]
	v_mul_f32_e32 v165, v172, v172
	v_mul_f32_e32 v169, v170, v170
	v_mul_f32_e32 v175, v171, v171
	v_mov_b32_e32 v164, v172
	v_mov_b32_e32 v166, v173
	v_mov_b32_e32 v168, v170
	v_mov_b32_e32 v174, v171
	v_pk_add_f32 v[164:165], v[164:165], v[166:167]
	v_pk_add_f32 v[166:167], v[168:169], v[174:175]
	s_nop 0
	v_pk_add_f32 v[164:165], v[164:165], v[166:167]
	s_nop 0
	v_pk_add_f32 v[162:163], v[162:163], v[164:165]
	s_waitcnt vmcnt(54)
	v_mov_b32_e32 v150, v230
	v_mov_b32_e32 v151, v231
	v_lshlrev_b32_e32 v164, 16, v150
	v_and_b32_e32 v165, 0xffff0000, v150
	v_lshlrev_b32_e32 v150, 16, v151
	v_and_b32_e32 v151, 0xffff0000, v151
	v_pk_fma_f32 v[150:151], v[150:151], s[24:25], v[30:31] op_sel_hi:[1,0,1]
	v_pk_fma_f32 v[164:165], v[164:165], s[24:25], v[28:29] op_sel_hi:[1,0,1]
	v_mul_f32_e32 v173, v150, v150
	v_mul_f32_e32 v169, v164, v164
	v_mul_f32_e32 v171, v165, v165
	v_mul_f32_e32 v175, v151, v151
	v_mov_b32_e32 v168, v164
	v_mov_b32_e32 v170, v165
	v_mov_b32_e32 v172, v150
	v_mov_b32_e32 v174, v151
	v_cvt_pk_bf16_f32 v166, v164, v165
	v_cvt_pk_bf16_f32 v167, v150, v151
	v_mul_f32_e32 v161, 0x417e0000, v150
	v_mul_f32_e32 v176, 0x417e0000, v151
	global_store_dwordx2 v[148:149], v[166:167], off offset:288
	v_pk_add_f32 v[148:149], v[168:169], v[170:171]
	v_pk_add_f32 v[150:151], v[172:173], v[174:175]
	v_mul_f32_e32 v143, 0x417e0000, v165
	v_pk_add_f32 v[148:149], v[148:149], v[150:151]
	v_mul_f32_e32 v133, 0x417e0000, v164
	v_pk_add_f32 v[148:149], v[162:163], v[148:149]
	ds_swizzle_b32 v150, v148 offset:swizzle(SWAP,16)
	ds_swizzle_b32 v151, v149 offset:swizzle(SWAP,16)
	v_med3_f32 v143, v143, s64, v160
	v_med3_f32 v133, v133, s64, v160
	v_med3_f32 v161, v161, s64, v160
	v_med3_f32 v164, v176, s64, v160
	v_rndne_f32_e32 v143, v143
	v_rndne_f32_e32 v133, v133
	v_rndne_f32_e32 v161, v161
	v_rndne_f32_e32 v164, v164
	v_cvt_i32_f32_e32 v143, v143
	v_cvt_i32_f32_e32 v133, v133
	v_cvt_i32_f32_sdwa v161, v161 dst_sel:WORD_1 dst_unused:UNUSED_PAD src0_sel:DWORD
	v_cvt_i32_f32_e32 v162, v164
	s_waitcnt lgkmcnt(0)
	v_pk_add_f32 v[148:149], v[148:149], v[150:151]
	ds_bpermute_b32 v150, v155, v148
	ds_bpermute_b32 v151, v155, v149
	v_lshlrev_b32_e32 v143, 8, v143
	v_and_b32_e32 v143, 0xff00, v143
	v_and_b32_e32 v161, 0xff0000, v161
	v_perm_b32 v133, v162, v133, s65
	v_or3_b32 v133, v133, v143, v161
	global_store_dword v[146:147], v133, off offset:144
	s_and_saveexec_b64 s[42:43], s[16:17]
	s_cbranch_execz .LBB0_1170
	s_lshl_b32 s44, s26, 2
	v_lshlrev_b64 v[144:145], 6, v[144:145]
	s_ashr_i32 s45, s44, 31
	v_lshl_add_u64 v[144:145], v[144:145], 0, s[44:45]
	v_or_b32_e32 v144, s3, v144
	s_waitcnt lgkmcnt(0)
	v_pk_add_f32 v[146:147], v[148:149], v[150:151]
	v_lshl_add_u64 v[144:145], v[144:145], 3, s[8:9]
	global_store_dwordx2 v[144:145], v[146:147], off
.LBB0_1170:
	s_or_b64 exec, exec, s[42:43]
	v_add_u32_e32 v144, 0xa0, v142
	v_ashrrev_i32_e32 v145, 31, v144
	v_lshlrev_b64 v[146:147], 12, v[144:145]
	v_lshl_add_u64 v[146:147], v[146:147], 0, v[140:141]
	v_lshlrev_b64 v[148:149], 1, v[146:147]
	s_waitcnt lgkmcnt(0)
	v_lshl_add_u64 v[150:151], s[0:1], 0, v[148:149]
	v_lshl_add_u64 v[146:147], s[10:11], 0, v[146:147]
	v_lshl_add_u64 v[148:149], s[6:7], 0, v[148:149]
	s_waitcnt vmcnt(55)
	v_mov_b32_e32 v162, v232
	v_mov_b32_e32 v163, v233
	v_lshlrev_b32_e32 v164, 16, v162
	v_and_b32_e32 v165, 0xffff0000, v162
	v_lshlrev_b32_e32 v162, 16, v163
	v_and_b32_e32 v163, 0xffff0000, v163
	v_pk_fma_f32 v[164:165], v[164:165], s[24:25], v[36:37] op_sel_hi:[1,0,1]
	v_pk_fma_f32 v[162:163], v[162:163], s[24:25], v[38:39] op_sel_hi:[1,0,1]
	v_mul_f32_e32 v143, 0x417e0000, v165
	v_mul_f32_e32 v133, 0x417e0000, v164
	v_mul_f32_e32 v161, 0x417e0000, v162
	v_mul_f32_e32 v168, 0x417e0000, v163
	v_med3_f32 v143, v143, s64, v160
	v_med3_f32 v133, v133, s64, v160
	v_med3_f32 v161, v161, s64, v160
	v_med3_f32 v168, v168, s64, v160
	v_rndne_f32_e32 v143, v143
	v_rndne_f32_e32 v133, v133
	v_rndne_f32_e32 v161, v161
	v_rndne_f32_e32 v168, v168
	v_cvt_i32_f32_e32 v143, v143
	v_cvt_i32_f32_e32 v133, v133
	v_cvt_i32_f32_sdwa v161, v161 dst_sel:WORD_1 dst_unused:UNUSED_PAD src0_sel:DWORD
	v_cvt_i32_f32_e32 v168, v168
	v_lshlrev_b32_e32 v143, 8, v143
	v_and_b32_e32 v143, 0xff00, v143
	v_and_b32_e32 v161, 0xff0000, v161
	v_perm_b32 v133, v168, v133, s65
	v_or3_b32 v133, v133, v143, v161
	v_cvt_pk_bf16_f32 v166, v164, v165
	v_cvt_pk_bf16_f32 v167, v162, v163
	global_store_dwordx2 v[148:149], v[166:167], off
	global_store_dword v[146:147], v133, off
	v_mul_f32_e32 v179, v164, v164
	v_mul_f32_e32 v181, v162, v162
	s_waitcnt vmcnt(56)
	v_mov_b32_e32 v166, v234
	v_mov_b32_e32 v167, v235
	v_lshlrev_b32_e32 v168, 16, v166
	v_and_b32_e32 v169, 0xffff0000, v166
	v_lshlrev_b32_e32 v166, 16, v167
	v_and_b32_e32 v167, 0xffff0000, v167
	v_pk_fma_f32 v[168:169], v[168:169], s[24:25], v[24:25] op_sel_hi:[1,0,1]
	v_pk_fma_f32 v[166:167], v[166:167], s[24:25], v[26:27] op_sel_hi:[1,0,1]
	v_mul_f32_e32 v143, 0x417e0000, v169
	v_mul_f32_e32 v133, 0x417e0000, v168
	v_mul_f32_e32 v161, 0x417e0000, v166
	v_mul_f32_e32 v172, 0x417e0000, v167
	v_med3_f32 v143, v143, s64, v160
	v_med3_f32 v133, v133, s64, v160
	v_med3_f32 v161, v161, s64, v160
	v_med3_f32 v172, v172, s64, v160
	v_rndne_f32_e32 v143, v143
	v_rndne_f32_e32 v133, v133
	v_rndne_f32_e32 v161, v161
	v_rndne_f32_e32 v172, v172
	v_cvt_i32_f32_e32 v143, v143
	v_cvt_i32_f32_e32 v133, v133
	v_cvt_i32_f32_sdwa v161, v161 dst_sel:WORD_1 dst_unused:UNUSED_PAD src0_sel:DWORD
	v_cvt_i32_f32_e32 v172, v172
	v_lshlrev_b32_e32 v143, 8, v143
	v_and_b32_e32 v143, 0xff00, v143
	v_and_b32_e32 v161, 0xff0000, v161
	v_perm_b32 v133, v172, v133, s65
	v_or3_b32 v133, v133, v143, v161
	v_cvt_pk_bf16_f32 v170, v168, v169
	v_cvt_pk_bf16_f32 v171, v166, v167
	global_store_dwordx2 v[148:149], v[170:171], off offset:32
	global_store_dword v[146:147], v133, off offset:16
	v_mul_f32_e32 v182, v166, v166
	v_mul_f32_e32 v177, v169, v169
	v_mov_b32_e32 v178, v168
	v_mov_b32_e32 v180, v166
	s_waitcnt vmcnt(57)
	v_mov_b32_e32 v170, v236
	v_mov_b32_e32 v171, v237
	v_lshlrev_b32_e32 v172, 16, v170
	v_and_b32_e32 v173, 0xffff0000, v170
	v_lshlrev_b32_e32 v170, 16, v171
	v_and_b32_e32 v171, 0xffff0000, v171
	v_pk_fma_f32 v[172:173], v[172:173], s[24:25], v[16:17] op_sel_hi:[1,0,1]
	v_pk_fma_f32 v[170:171], v[170:171], s[24:25], v[18:19] op_sel_hi:[1,0,1]
	v_mul_f32_e32 v143, 0x417e0000, v173
	v_mul_f32_e32 v133, 0x417e0000, v172
	v_mul_f32_e32 v161, 0x417e0000, v170
	v_mul_f32_e32 v176, 0x417e0000, v171
	v_med3_f32 v143, v143, s64, v160
	v_med3_f32 v133, v133, s64, v160
	v_med3_f32 v161, v161, s64, v160
	v_med3_f32 v176, v176, s64, v160
	v_rndne_f32_e32 v143, v143
	v_rndne_f32_e32 v133, v133
	v_rndne_f32_e32 v161, v161
	v_rndne_f32_e32 v176, v176
	v_cvt_i32_f32_e32 v143, v143
	v_cvt_i32_f32_e32 v133, v133
	v_cvt_i32_f32_sdwa v161, v161 dst_sel:WORD_1 dst_unused:UNUSED_PAD src0_sel:DWORD
	v_cvt_i32_f32_e32 v176, v176
	v_lshlrev_b32_e32 v143, 8, v143
	v_and_b32_e32 v143, 0xff00, v143
	v_and_b32_e32 v161, 0xff0000, v161
	v_perm_b32 v133, v176, v133, s65
	v_or3_b32 v133, v133, v143, v161
	v_cvt_pk_bf16_f32 v174, v172, v173
	v_cvt_pk_bf16_f32 v175, v170, v171
	global_store_dwordx2 v[148:149], v[174:175], off offset:256
	global_store_dword v[146:147], v133, off offset:128
	v_add_f32_e32 v174, v164, v165
	v_add_f32_e32 v176, v162, v163
	v_mul_f32_e32 v165, v165, v165
	v_mul_f32_e32 v163, v163, v163
	v_mul_f32_e32 v175, v168, v168
	v_mov_b32_e32 v164, v169
	v_mov_b32_e32 v162, v167
	v_pk_fma_f32 v[166:167], v[166:167], v[166:167], v[182:183] op_sel_hi:[1,1,0]
	v_pk_add_f32 v[164:165], v[178:179], v[164:165]
	v_pk_add_f32 v[162:163], v[180:181], v[162:163]
	v_pk_add_f32 v[168:169], v[174:175], v[176:177]
	v_mov_b32_e32 v133, v167
	v_pk_add_f32 v[162:163], v[164:165], v[162:163]
	v_pk_add_f32 v[164:165], v[168:169], v[132:133]
	v_mul_f32_e32 v167, v173, v173
	v_pk_add_f32 v[162:163], v[162:163], v[164:165]
	v_mul_f32_e32 v165, v172, v172
	v_mul_f32_e32 v169, v170, v170
	v_mul_f32_e32 v175, v171, v171
	v_mov_b32_e32 v164, v172
	v_mov_b32_e32 v166, v173
	v_mov_b32_e32 v168, v170
	v_mov_b32_e32 v174, v171
	v_pk_add_f32 v[164:165], v[164:165], v[166:167]
	v_pk_add_f32 v[166:167], v[168:169], v[174:175]
	s_nop 0
	v_pk_add_f32 v[164:165], v[164:165], v[166:167]
	s_nop 0
	v_pk_add_f32 v[162:163], v[162:163], v[164:165]
	s_waitcnt vmcnt(58)
	v_mov_b32_e32 v150, v238
	v_mov_b32_e32 v151, v239
	v_lshlrev_b32_e32 v164, 16, v150
	v_and_b32_e32 v165, 0xffff0000, v150
	v_lshlrev_b32_e32 v150, 16, v151
	v_and_b32_e32 v151, 0xffff0000, v151
	v_pk_fma_f32 v[150:151], v[150:151], s[24:25], v[14:15] op_sel_hi:[1,0,1]
	v_pk_fma_f32 v[164:165], v[164:165], s[24:25], v[12:13] op_sel_hi:[1,0,1]
	v_mul_f32_e32 v173, v150, v150
	v_mul_f32_e32 v169, v164, v164
	v_mul_f32_e32 v171, v165, v165
	v_mul_f32_e32 v175, v151, v151
	v_mov_b32_e32 v168, v164
	v_mov_b32_e32 v170, v165
	v_mov_b32_e32 v172, v150
	v_mov_b32_e32 v174, v151
	v_cvt_pk_bf16_f32 v166, v164, v165
	v_cvt_pk_bf16_f32 v167, v150, v151
	v_mul_f32_e32 v161, 0x417e0000, v150
	v_mul_f32_e32 v176, 0x417e0000, v151
	global_store_dwordx2 v[148:149], v[166:167], off offset:288
	v_pk_add_f32 v[148:149], v[168:169], v[170:171]
	v_pk_add_f32 v[150:151], v[172:173], v[174:175]
	v_mul_f32_e32 v143, 0x417e0000, v165
	v_pk_add_f32 v[148:149], v[148:149], v[150:151]
	v_mul_f32_e32 v133, 0x417e0000, v164
	v_pk_add_f32 v[148:149], v[162:163], v[148:149]
	ds_swizzle_b32 v150, v148 offset:swizzle(SWAP,16)
	ds_swizzle_b32 v151, v149 offset:swizzle(SWAP,16)
	v_med3_f32 v143, v143, s64, v160
	v_med3_f32 v133, v133, s64, v160
	v_med3_f32 v161, v161, s64, v160
	v_med3_f32 v164, v176, s64, v160
	v_rndne_f32_e32 v143, v143
	v_rndne_f32_e32 v133, v133
	v_rndne_f32_e32 v161, v161
	v_rndne_f32_e32 v164, v164
	v_cvt_i32_f32_e32 v143, v143
	v_cvt_i32_f32_e32 v133, v133
	v_cvt_i32_f32_sdwa v161, v161 dst_sel:WORD_1 dst_unused:UNUSED_PAD src0_sel:DWORD
	v_cvt_i32_f32_e32 v162, v164
	s_waitcnt lgkmcnt(0)
	v_pk_add_f32 v[148:149], v[148:149], v[150:151]
	ds_bpermute_b32 v150, v155, v148
	ds_bpermute_b32 v151, v155, v149
	v_lshlrev_b32_e32 v143, 8, v143
	v_and_b32_e32 v143, 0xff00, v143
	v_and_b32_e32 v161, 0xff0000, v161
	v_perm_b32 v133, v162, v133, s65
	v_or3_b32 v133, v133, v143, v161
	global_store_dword v[146:147], v133, off offset:144
	s_and_saveexec_b64 s[42:43], s[16:17]
	s_cbranch_execz .LBB0_1172
	s_lshl_b32 s44, s26, 2
	v_lshlrev_b64 v[144:145], 6, v[144:145]
	s_ashr_i32 s45, s44, 31
	v_lshl_add_u64 v[144:145], v[144:145], 0, s[44:45]
	v_or_b32_e32 v144, s3, v144
	s_waitcnt lgkmcnt(0)
	v_pk_add_f32 v[146:147], v[148:149], v[150:151]
	v_lshl_add_u64 v[144:145], v[144:145], 3, s[8:9]
	global_store_dwordx2 v[144:145], v[146:147], off
.LBB0_1172:
	s_or_b64 exec, exec, s[42:43]
	v_add_u32_e32 v142, 0xb0, v142
	v_ashrrev_i32_e32 v143, 31, v142
	v_lshlrev_b64 v[144:145], 12, v[142:143]
	v_lshl_add_u64 v[144:145], v[144:145], 0, v[140:141]
	v_lshlrev_b64 v[146:147], 1, v[144:145]
	v_lshl_add_u64 v[148:149], s[0:1], 0, v[146:147]
	s_waitcnt lgkmcnt(0)
	v_lshl_add_u64 v[146:147], s[6:7], 0, v[146:147]
	v_lshl_add_u64 v[144:145], s[10:11], 0, v[144:145]
	s_waitcnt vmcnt(59)
	v_mov_b32_e32 v150, v240
	v_mov_b32_e32 v151, v241
	v_lshlrev_b32_e32 v162, 16, v150
	v_and_b32_e32 v163, 0xffff0000, v150
	v_lshlrev_b32_e32 v150, 16, v151
	v_and_b32_e32 v151, 0xffff0000, v151
	v_pk_fma_f32 v[162:163], v[162:163], s[24:25], v[20:21] op_sel_hi:[1,0,1]
	v_pk_fma_f32 v[150:151], v[150:151], s[24:25], v[22:23] op_sel_hi:[1,0,1]
	v_mul_f32_e32 v161, 0x417e0000, v163
	v_mul_f32_e32 v133, 0x417e0000, v162
	v_mul_f32_e32 v166, 0x417e0000, v150
	v_mul_f32_e32 v167, 0x417e0000, v151
	v_med3_f32 v161, v161, s64, v160
	v_med3_f32 v133, v133, s64, v160
	v_med3_f32 v166, v166, s64, v160
	v_med3_f32 v167, v167, s64, v160
	v_rndne_f32_e32 v161, v161
	v_rndne_f32_e32 v133, v133
	v_rndne_f32_e32 v166, v166
	v_rndne_f32_e32 v167, v167
	v_cvt_i32_f32_e32 v161, v161
	v_cvt_i32_f32_e32 v133, v133
	v_cvt_i32_f32_sdwa v166, v166 dst_sel:WORD_1 dst_unused:UNUSED_PAD src0_sel:DWORD
	v_cvt_i32_f32_e32 v167, v167
	v_cvt_pk_bf16_f32 v164, v162, v163
	v_lshlrev_b32_e32 v161, 8, v161
	v_cvt_pk_bf16_f32 v165, v150, v151
	global_store_dwordx2 v[146:147], v[164:165], off
	v_and_b32_e32 v164, 0xff0000, v166
	v_perm_b32 v133, v167, v133, s65
	v_and_b32_e32 v161, 0xff00, v161
	v_or3_b32 v133, v133, v161, v164
	global_store_dword v[144:145], v133, off
	v_mul_f32_e32 v177, v162, v162
	v_mul_f32_e32 v179, v150, v150
	s_waitcnt vmcnt(60)
	v_mov_b32_e32 v164, v242
	v_mov_b32_e32 v165, v243
	v_lshlrev_b32_e32 v166, 16, v164
	v_and_b32_e32 v167, 0xffff0000, v164
	v_lshlrev_b32_e32 v164, 16, v165
	v_and_b32_e32 v165, 0xffff0000, v165
	v_pk_fma_f32 v[166:167], v[166:167], s[24:25], v[8:9] op_sel_hi:[1,0,1]
	v_pk_fma_f32 v[164:165], v[164:165], s[24:25], v[10:11] op_sel_hi:[1,0,1]
	v_mul_f32_e32 v161, 0x417e0000, v167
	v_mul_f32_e32 v133, 0x417e0000, v166
	v_mul_f32_e32 v170, 0x417e0000, v164
	v_mul_f32_e32 v171, 0x417e0000, v165
	v_med3_f32 v161, v161, s64, v160
	v_med3_f32 v133, v133, s64, v160
	v_med3_f32 v170, v170, s64, v160
	v_med3_f32 v171, v171, s64, v160
	v_rndne_f32_e32 v161, v161
	v_rndne_f32_e32 v133, v133
	v_rndne_f32_e32 v170, v170
	v_rndne_f32_e32 v171, v171
	v_cvt_i32_f32_e32 v161, v161
	v_cvt_i32_f32_e32 v133, v133
	v_cvt_i32_f32_sdwa v170, v170 dst_sel:WORD_1 dst_unused:UNUSED_PAD src0_sel:DWORD
	v_cvt_i32_f32_e32 v171, v171
	v_cvt_pk_bf16_f32 v168, v166, v167
	v_lshlrev_b32_e32 v161, 8, v161
	v_cvt_pk_bf16_f32 v169, v164, v165
	global_store_dwordx2 v[146:147], v[168:169], off offset:32
	v_and_b32_e32 v168, 0xff0000, v170
	v_perm_b32 v133, v171, v133, s65
	v_and_b32_e32 v161, 0xff00, v161
	v_or3_b32 v133, v133, v161, v168
	global_store_dword v[144:145], v133, off offset:16
	v_mul_f32_e32 v180, v164, v164
	v_mov_b32_e32 v176, v166
	v_mov_b32_e32 v178, v164
	s_waitcnt vmcnt(61)
	v_mov_b32_e32 v168, v244
	v_mov_b32_e32 v169, v245
	v_lshlrev_b32_e32 v170, 16, v168
	v_and_b32_e32 v171, 0xffff0000, v168
	v_lshlrev_b32_e32 v168, 16, v169
	v_and_b32_e32 v169, 0xffff0000, v169
	v_pk_fma_f32 v[170:171], v[170:171], s[24:25], v[4:5] op_sel_hi:[1,0,1]
	v_pk_fma_f32 v[168:169], v[168:169], s[24:25], v[6:7] op_sel_hi:[1,0,1]
	v_mul_f32_e32 v161, 0x417e0000, v171
	v_mul_f32_e32 v133, 0x417e0000, v170
	v_mul_f32_e32 v174, 0x417e0000, v168
	v_mul_f32_e32 v175, 0x417e0000, v169
	v_med3_f32 v161, v161, s64, v160
	v_med3_f32 v133, v133, s64, v160
	v_med3_f32 v174, v174, s64, v160
	v_med3_f32 v175, v175, s64, v160
	v_rndne_f32_e32 v161, v161
	v_rndne_f32_e32 v133, v133
	v_rndne_f32_e32 v174, v174
	v_rndne_f32_e32 v175, v175
	v_cvt_i32_f32_e32 v161, v161
	v_cvt_i32_f32_e32 v133, v133
	v_cvt_i32_f32_sdwa v174, v174 dst_sel:WORD_1 dst_unused:UNUSED_PAD src0_sel:DWORD
	v_cvt_i32_f32_e32 v175, v175
	v_cvt_pk_bf16_f32 v172, v170, v171
	v_lshlrev_b32_e32 v161, 8, v161
	v_cvt_pk_bf16_f32 v173, v168, v169
	global_store_dwordx2 v[146:147], v[172:173], off offset:256
	v_and_b32_e32 v172, 0xff0000, v174
	v_perm_b32 v133, v175, v133, s65
	v_and_b32_e32 v161, 0xff00, v161
	v_or3_b32 v133, v133, v161, v172
	global_store_dword v[144:145], v133, off offset:128
	v_add_f32_e32 v172, v162, v163
	v_add_f32_e32 v174, v150, v151
	v_mul_f32_e32 v163, v163, v163
	v_mul_f32_e32 v151, v151, v151
	v_mul_f32_e32 v173, v166, v166
	v_mul_f32_e32 v175, v167, v167
	v_mov_b32_e32 v162, v167
	v_mov_b32_e32 v150, v165
	v_pk_fma_f32 v[164:165], v[164:165], v[164:165], v[180:181] op_sel_hi:[1,1,0]
	v_pk_add_f32 v[162:163], v[176:177], v[162:163]
	v_pk_add_f32 v[150:151], v[178:179], v[150:151]
	v_pk_add_f32 v[166:167], v[172:173], v[174:175]
	v_mov_b32_e32 v133, v165
	v_pk_add_f32 v[150:151], v[162:163], v[150:151]
	v_pk_add_f32 v[162:163], v[166:167], v[132:133]
	v_mul_f32_e32 v165, v171, v171
	v_pk_add_f32 v[150:151], v[150:151], v[162:163]
	v_mul_f32_e32 v163, v170, v170
	v_mul_f32_e32 v167, v168, v168
	v_mul_f32_e32 v173, v169, v169
	v_mov_b32_e32 v162, v170
	v_mov_b32_e32 v164, v171
	v_mov_b32_e32 v166, v168
	v_mov_b32_e32 v172, v169
	v_pk_add_f32 v[162:163], v[162:163], v[164:165]
	v_pk_add_f32 v[164:165], v[166:167], v[172:173]
	s_nop 0
	v_pk_add_f32 v[162:163], v[162:163], v[164:165]
	s_nop 0
	v_pk_add_f32 v[150:151], v[150:151], v[162:163]
	s_waitcnt vmcnt(62)
	v_mov_b32_e32 v148, v246
	v_mov_b32_e32 v149, v247
	v_lshlrev_b32_e32 v162, 16, v148
	v_and_b32_e32 v163, 0xffff0000, v148
	v_lshlrev_b32_e32 v148, 16, v149
	v_and_b32_e32 v149, 0xffff0000, v149
	v_pk_fma_f32 v[148:149], v[148:149], s[24:25], v[2:3] op_sel_hi:[1,0,1]
	v_pk_fma_f32 v[162:163], v[162:163], s[24:25], v[0:1] op_sel_hi:[1,0,1]
	v_mul_f32_e32 v171, v148, v148
	v_mul_f32_e32 v167, v162, v162
	v_mul_f32_e32 v169, v163, v163
	v_mul_f32_e32 v173, v149, v149
	v_mov_b32_e32 v166, v162
	v_mov_b32_e32 v168, v163
	v_mov_b32_e32 v170, v148
	v_mov_b32_e32 v172, v149
	v_cvt_pk_bf16_f32 v164, v162, v163
	v_cvt_pk_bf16_f32 v165, v148, v149
	v_mul_f32_e32 v174, 0x417e0000, v148
	v_mul_f32_e32 v175, 0x417e0000, v149
	global_store_dwordx2 v[146:147], v[164:165], off offset:288
	v_pk_add_f32 v[146:147], v[166:167], v[168:169]
	v_pk_add_f32 v[148:149], v[170:171], v[172:173]
	v_mul_f32_e32 v161, 0x417e0000, v163
	v_pk_add_f32 v[146:147], v[146:147], v[148:149]
	v_mul_f32_e32 v133, 0x417e0000, v162
	v_pk_add_f32 v[146:147], v[150:151], v[146:147]
	ds_swizzle_b32 v148, v146 offset:swizzle(SWAP,16)
	ds_swizzle_b32 v149, v147 offset:swizzle(SWAP,16)
	v_med3_f32 v161, v161, s64, v160
	v_med3_f32 v133, v133, s64, v160
	v_med3_f32 v162, v174, s64, v160
	v_med3_f32 v163, v175, s64, v160
	v_rndne_f32_e32 v161, v161
	v_rndne_f32_e32 v133, v133
	v_rndne_f32_e32 v162, v162
	v_rndne_f32_e32 v163, v163
	v_cvt_i32_f32_e32 v161, v161
	v_cvt_i32_f32_e32 v133, v133
	v_cvt_i32_f32_sdwa v150, v162 dst_sel:WORD_1 dst_unused:UNUSED_PAD src0_sel:DWORD
	v_cvt_i32_f32_e32 v151, v163
	s_waitcnt lgkmcnt(0)
	v_pk_add_f32 v[146:147], v[146:147], v[148:149]
	ds_bpermute_b32 v148, v155, v146
	ds_bpermute_b32 v149, v155, v147
	v_lshlrev_b32_e32 v161, 8, v161
	v_and_b32_e32 v161, 0xff00, v161
	v_and_b32_e32 v150, 0xff0000, v150
	v_perm_b32 v133, v151, v133, s65
	v_or3_b32 v133, v133, v161, v150
	global_store_dword v[144:145], v133, off offset:144
	s_and_saveexec_b64 s[42:43], s[16:17]
	s_cbranch_execz .LBB0_1174
	s_lshl_b32 s44, s26, 2
	v_lshlrev_b64 v[142:143], 6, v[142:143]
	s_ashr_i32 s45, s44, 31
	v_lshl_add_u64 v[142:143], v[142:143], 0, s[44:45]
	v_or_b32_e32 v142, s3, v142
	s_waitcnt lgkmcnt(0)
	v_pk_add_f32 v[144:145], v[146:147], v[148:149]
	v_lshl_add_u64 v[142:143], v[142:143], 3, s[8:9]
	global_store_dwordx2 v[142:143], v[144:145], off

	.amdhsa_kernel _Z9hymba_fwd4Args
		.amdhsa_group_segment_fixed_size 0
		.amdhsa_private_segment_fixed_size 0
		.amdhsa_kernarg_size 464
		.amdhsa_user_sgpr_count 2
		.amdhsa_user_sgpr_dispatch_ptr 0
		.amdhsa_user_sgpr_queue_ptr 0
		.amdhsa_user_sgpr_kernarg_segment_ptr 1
		.amdhsa_user_sgpr_dispatch_id 0
		.amdhsa_user_sgpr_kernarg_preload_length 0
		.amdhsa_user_sgpr_kernarg_preload_offset 0
		.amdhsa_user_sgpr_private_segment_size 0
		.amdhsa_uses_dynamic_stack 0
		.amdhsa_enable_private_segment 0
		.amdhsa_system_sgpr_workgroup_id_x 1
		.amdhsa_system_sgpr_workgroup_id_y 0
		.amdhsa_system_sgpr_workgroup_id_z 0
		.amdhsa_system_sgpr_workgroup_info 0
		.amdhsa_system_vgpr_workitem_id 0
		.amdhsa_next_free_vgpr 251
		.amdhsa_next_free_sgpr 102
		.amdhsa_accum_offset 252
		.amdhsa_reserve_vcc 1
		.amdhsa_float_round_mode_32 0
		.amdhsa_float_round_mode_16_64 0
		.amdhsa_float_denorm_mode_32 3
		.amdhsa_float_denorm_mode_16_64 3
		.amdhsa_dx10_clamp 1
		.amdhsa_ieee_mode 1
		.amdhsa_fp16_overflow 0
		.amdhsa_tg_split 0
		.amdhsa_exception_fp_ieee_invalid_op 0
		.amdhsa_exception_fp_denorm_src 0
		.amdhsa_exception_fp_ieee_div_zero 0
		.amdhsa_exception_fp_ieee_overflow 0
		.amdhsa_exception_fp_ieee_underflow 0
		.amdhsa_exception_fp_ieee_inexact 0
		.amdhsa_exception_int_div_zero 0
	.end_amdhsa_kernel

.Lfunc_end0:
	.size	_Z9hymba_fwd4Args, .Lfunc_end0-_Z9hymba_fwd4Args
	.set _Z9hymba_fwd4Args.num_vgpr, 251
	.set _Z9hymba_fwd4Args.num_agpr, 0
	.set _Z9hymba_fwd4Args.numbered_sgpr, 102
	.set _Z9hymba_fwd4Args.num_named_barrier, 0
	.set _Z9hymba_fwd4Args.private_seg_size, 0
	.set _Z9hymba_fwd4Args.uses_vcc, 1
	.set _Z9hymba_fwd4Args.uses_flat_scratch, 0
	.set _Z9hymba_fwd4Args.has_dyn_sized_stack, 0
	.set _Z9hymba_fwd4Args.has_recursion, 0
	.set _Z9hymba_fwd4Args.has_indirect_call, 0

amdhsa.kernels:
  - .agpr_count:     0
    .args:
      - .offset:         0
        .size:           208
        .value_kind:     by_value
      - .offset:         208
        .size:           4
        .value_kind:     hidden_block_count_x
      - .offset:         212
        .size:           4
        .value_kind:     hidden_block_count_y
      - .offset:         216
        .size:           4
        .value_kind:     hidden_block_count_z
      - .offset:         220
        .size:           2
        .value_kind:     hidden_group_size_x
      - .offset:         222
        .size:           2
        .value_kind:     hidden_group_size_y
      - .offset:         224
        .size:           2
        .value_kind:     hidden_group_size_z
      - .offset:         226
        .size:           2
        .value_kind:     hidden_remainder_x
      - .offset:         228
        .size:           2
        .value_kind:     hidden_remainder_y
      - .offset:         230
        .size:           2
        .value_kind:     hidden_remainder_z
      - .offset:         248
        .size:           8
        .value_kind:     hidden_global_offset_x
      - .offset:         256
        .size:           8
        .value_kind:     hidden_global_offset_y
      - .offset:         264
        .size:           8
        .value_kind:     hidden_global_offset_z
      - .offset:         272
        .size:           2
        .value_kind:     hidden_grid_dims
      - .offset:         328
        .size:           4
        .value_kind:     hidden_dynamic_lds_size
    .group_segment_fixed_size: 0
    .kernarg_segment_align: 8
    .kernarg_segment_size: 464
    .language:       OpenCL C
    .language_version:
      - 2
      - 0
    .max_flat_workgroup_size: 512
    .name:           _Z9hymba_fwd4Args
    .private_segment_fixed_size: 0
    .sgpr_count:     108
    .sgpr_spill_count: 60
    .symbol:         _Z9hymba_fwd4Args.kd
    .uniform_work_group_size: 1
    .uses_dynamic_stack: false
    .vgpr_count:     251
    .vgpr_spill_count: 0
    .wavefront_size: 64
